# de-serialised residual loads in both out-projection GEMM epilogues (were load-wait-store one at a time); hand-written norm1 phase with next-token prefetch
# speedup vs baseline: 1.0192x; 1.0192x over previous
; #define PG8_STAGE(bufoff, gbase, voff) do { _Pragma("unroll") for (int _i = 0; _i < 2; ++_i) \
;         __builtin_amdgcn_global_load_lds((const unsigned*)((const char*)(gbase) + (voff)[_i]), (LAS unsigned*)(lds + (bufoff) + ldsw + _i * 8192), 16, 0, 0); } while (0)
; #define PG8_LDA(dst, b, h) do { _Pragma("unroll") for (int m = 0; m < 4; ++m) _Pragma("unroll") for (int k = 0; k < 2; ++k) dst[m][k] = *(const LAS bf16x8*)(lds + PG8_SA(b, h) + aoff + m * 2048 + k * 1024); } while (0)
; #define PG8_LDB(dst, b, h) do { _Pragma("unroll") for (int n = 0; n < 2; ++n) _Pragma("unroll") for (int k = 0; k < 2; ++k) dst[n][k] = *(const LAS bf16x8*)(lds + PG8_SB(b, h) + boff + n * 2048 + k * 1024); } while (0)
; #define PG8_MMA(ai, bj, At, Bt) do { __builtin_amdgcn_s_setprio(1); _Pragma("unroll") for (int m = 0; m < 4; ++m) _Pragma("unroll") for (int n = 0; n < 2; ++n) _Pragma("unroll") for (int k = 0; k < 2; ++k) \
;         acc[ai][bj][m][n] = __builtin_amdgcn_mfma_f32_16x16x32_bf16(Bt[n][k], At[m][k], acc[ai][bj][m][n], 0, 0, 0); __builtin_amdgcn_s_setprio(0); } while (0)
; #define PG8_WAIT_V(n) asm volatile("s_waitcnt vmcnt(" #n ")" ::: "memory")
; #define PG8_WAIT_L(n) asm volatile("s_waitcnt lgkmcnt(" #n ")" ::: "memory")
; #define PG8_BAR __builtin_amdgcn_s_barrier()
; #define PG8_SCHED __builtin_amdgcn_sched_barrier(0)
; template <class Epi, class Sched>
; DI void gemm_phase(LAS unsigned char* lds, const Gemm g, const Sched& S, const Epi& E) {
;     ...
;             PG8_LDB(B0, 0, 0); PG8_SCHED; PG8_LDA(At, 0, 0); PG8_STAGE(PG8_SA(1, 1), a1 + hstep, voffA);
;             PG8_WAIT_L(8); PG8_BAR; PG8_WAIT_L(0); PG8_MMA(0, 0, At, B0); PG8_BAR; PG8_SCHED;
;             PG8_LDB(B1, 0, 1); PG8_STAGE(PG8_SB(0, 0), b2, voffB);
;             PG8_BAR; PG8_WAIT_L(0); PG8_MMA(0, 1, At, B1); PG8_BAR;
;             PG8_LDA(At, 0, 1); PG8_STAGE(PG8_SA(0, 0), a2, voffA);
;             PG8_BAR; PG8_WAIT_L(0); PG8_MMA(1, 0, At, B0); PG8_BAR; PG8_SCHED;
;             PG8_STAGE(PG8_SB(0, 1), b2 + hstep, voffB);
;             PG8_WAIT_V(6); PG8_BAR; PG8_MMA(1, 1, At, B1); PG8_BAR;
;             PG8_LDB(B0, 1, 0); PG8_SCHED; PG8_LDA(At, 1, 0); PG8_STAGE(PG8_SA(0, 1), a2 + hstep, voffA);
;             PG8_WAIT_L(8); PG8_BAR; PG8_WAIT_L(0); PG8_MMA(0, 0, At, B0); PG8_BAR; PG8_SCHED;
.LBB0_1007:
	ds_read_b128 v[140:143], v147
	ds_read_b128 v[154:157], v147 offset:1024
	ds_read_b128 v[158:161], v147 offset:2048
	ds_read_b128 v[164:167], v147 offset:3072
	s_add_u32 s24, s22, 0xfffc0080
	s_addc_u32 s25, s23, -1
	s_cmp_eq_u32 s66, 12
	s_cselect_b32 s27, s47, s25
	s_cselect_b32 s26, s53, s24
	s_cselect_b32 s25, s54, s59
	s_cselect_b32 s24, s55, s58
	s_mov_b32 m0, s36
	v_lshl_add_u64 v[150:151], s[22:23], 0, v[136:137]
	ds_read_b128 v[168:171], v148
	ds_read_b128 v[172:175], v148 offset:1024
	ds_read_b128 v[176:179], v148 offset:2048
	ds_read_b128 v[180:183], v148 offset:3072
	ds_read_b128 v[184:187], v148 offset:4096
	ds_read_b128 v[188:191], v148 offset:5120
	ds_read_b128 v[192:195], v148 offset:6144
	ds_read_b128 v[198:201], v148 offset:7168
	global_load_lds_dwordx4 v[150:151], off
	v_lshl_add_u64 v[150:151], s[22:23], 0, v[138:139]
	s_mov_b32 m0, s37
	s_nop 0
	global_load_lds_dwordx4 v[150:151], off
	s_waitcnt lgkmcnt(8)
	s_barrier
	s_waitcnt lgkmcnt(0)
	s_setprio 1
	s_waitcnt lgkmcnt(0)
	v_mfma_f32_16x16x32_bf16 v[126:129], v[140:143], v[168:171], v[126:129]
	v_mfma_f32_16x16x32_bf16 v[122:125], v[158:161], v[168:171], v[122:125]
	v_mfma_f32_16x16x32_bf16 v[114:117], v[140:143], v[176:179], v[114:117]
	v_mfma_f32_16x16x32_bf16 v[106:109], v[158:161], v[176:179], v[106:109]
	v_mfma_f32_16x16x32_bf16 v[98:101], v[140:143], v[184:187], v[98:101]
	v_mfma_f32_16x16x32_bf16 v[90:93], v[158:161], v[184:187], v[90:93]
	v_mfma_f32_16x16x32_bf16 v[82:85], v[140:143], v[192:195], v[82:85]
	v_mfma_f32_16x16x32_bf16 v[74:77], v[158:161], v[192:195], v[74:77]
	v_mfma_f32_16x16x32_bf16 v[126:129], v[154:157], v[172:175], v[126:129]
	v_mfma_f32_16x16x32_bf16 v[122:125], v[164:167], v[172:175], v[122:125]
	v_mfma_f32_16x16x32_bf16 v[114:117], v[154:157], v[180:183], v[114:117]
	v_mfma_f32_16x16x32_bf16 v[106:109], v[164:167], v[180:183], v[106:109]
	v_mfma_f32_16x16x32_bf16 v[98:101], v[154:157], v[188:191], v[98:101]
	v_mfma_f32_16x16x32_bf16 v[90:93], v[164:167], v[188:191], v[90:93]
	v_mfma_f32_16x16x32_bf16 v[82:85], v[154:157], v[198:201], v[82:85]
	v_mfma_f32_16x16x32_bf16 v[74:77], v[164:167], v[198:201], v[74:77]
	s_setprio 0
	s_barrier
	s_mov_b32 m0, s38
	v_lshl_add_u64 v[150:151], s[24:25], 0, v[132:133]
	ds_read_b128 v[202:205], v149
	ds_read_b128 v[206:209], v149 offset:1024
	ds_read_b128 v[210:213], v149 offset:2048
	ds_read_b128 v[214:217], v149 offset:3072
	global_load_lds_dwordx4 v[150:151], off
	v_lshl_add_u64 v[218:219], s[24:25], 0, v[130:131]
	s_mov_b32 m0, s39
	s_nop 0
	global_load_lds_dwordx4 v[218:219], off
	s_barrier
	s_waitcnt lgkmcnt(0)
	s_setprio 1
	s_waitcnt lgkmcnt(0)
	v_mfma_f32_16x16x32_bf16 v[118:121], v[202:205], v[168:171], v[118:121]
	v_mfma_f32_16x16x32_bf16 v[110:113], v[210:213], v[168:171], v[110:113]
	v_mfma_f32_16x16x32_bf16 v[102:105], v[202:205], v[176:179], v[102:105]
	v_mfma_f32_16x16x32_bf16 v[94:97], v[210:213], v[176:179], v[94:97]
	v_mfma_f32_16x16x32_bf16 v[86:89], v[202:205], v[184:187], v[86:89]
	v_mfma_f32_16x16x32_bf16 v[78:81], v[210:213], v[184:187], v[78:81]
	v_mfma_f32_16x16x32_bf16 v[70:73], v[202:205], v[192:195], v[70:73]
	v_mfma_f32_16x16x32_bf16 v[66:69], v[210:213], v[192:195], v[66:69]
	v_mfma_f32_16x16x32_bf16 v[118:121], v[206:209], v[172:175], v[118:121]
	v_mfma_f32_16x16x32_bf16 v[110:113], v[214:217], v[172:175], v[110:113]
	v_mfma_f32_16x16x32_bf16 v[102:105], v[206:209], v[180:183], v[102:105]
	v_mfma_f32_16x16x32_bf16 v[94:97], v[214:217], v[180:183], v[94:97]
	v_mfma_f32_16x16x32_bf16 v[86:89], v[206:209], v[188:191], v[86:89]
	v_mfma_f32_16x16x32_bf16 v[78:81], v[214:217], v[188:191], v[78:81]
	v_mfma_f32_16x16x32_bf16 v[70:73], v[206:209], v[198:201], v[70:73]
	v_mfma_f32_16x16x32_bf16 v[66:69], v[214:217], v[198:201], v[66:69]
	s_setprio 0
	s_mov_b32 m0, s13
	v_lshl_add_u64 v[220:221], s[26:27], 0, v[132:133]
	s_barrier
	ds_read_b128 v[168:171], v148 offset:16384
	ds_read_b128 v[172:175], v148 offset:17408
	ds_read_b128 v[176:179], v148 offset:18432
	ds_read_b128 v[180:183], v148 offset:19456
	ds_read_b128 v[184:187], v148 offset:20480
	ds_read_b128 v[188:191], v148 offset:21504
	ds_read_b128 v[192:195], v148 offset:22528
	ds_read_b128 v[198:201], v148 offset:23552
	global_load_lds_dwordx4 v[220:221], off
	v_lshl_add_u64 v[222:223], s[26:27], 0, v[130:131]
	s_mov_b32 m0, s28
	s_nop 0
	global_load_lds_dwordx4 v[222:223], off
	s_barrier
	s_waitcnt lgkmcnt(0)
	s_setprio 1
	s_waitcnt lgkmcnt(0)
	v_mfma_f32_16x16x32_bf16 v[62:65], v[140:143], v[168:171], v[62:65]
	v_mfma_f32_16x16x32_bf16 v[58:61], v[158:161], v[168:171], v[58:61]
	v_mfma_f32_16x16x32_bf16 v[50:53], v[140:143], v[176:179], v[50:53]
	v_mfma_f32_16x16x32_bf16 v[42:45], v[158:161], v[176:179], v[42:45]
	v_mfma_f32_16x16x32_bf16 v[34:37], v[140:143], v[184:187], v[34:37]
	v_mfma_f32_16x16x32_bf16 v[26:29], v[158:161], v[184:187], v[26:29]
	v_mfma_f32_16x16x32_bf16 v[18:21], v[140:143], v[192:195], v[18:21]
	v_mfma_f32_16x16x32_bf16 v[10:13], v[158:161], v[192:195], v[10:13]
	v_mfma_f32_16x16x32_bf16 v[62:65], v[154:157], v[172:175], v[62:65]
	v_mfma_f32_16x16x32_bf16 v[58:61], v[164:167], v[172:175], v[58:61]
	v_mfma_f32_16x16x32_bf16 v[50:53], v[154:157], v[180:183], v[50:53]
	v_mfma_f32_16x16x32_bf16 v[42:45], v[164:167], v[180:183], v[42:45]
	v_mfma_f32_16x16x32_bf16 v[34:37], v[154:157], v[188:191], v[34:37]
	v_mfma_f32_16x16x32_bf16 v[26:29], v[164:167], v[188:191], v[26:29]
	v_mfma_f32_16x16x32_bf16 v[18:21], v[154:157], v[198:201], v[18:21]
	v_mfma_f32_16x16x32_bf16 v[10:13], v[164:167], v[198:201], v[10:13]
	s_setprio 0
	s_barrier
; #define PG8_STAGE(bufoff, gbase, voff) do { _Pragma("unroll") for (int _i = 0; _i < 2; ++_i) \
;         __builtin_amdgcn_global_load_lds((const unsigned*)((const char*)(gbase) + (voff)[_i]), (LAS unsigned*)(lds + (bufoff) + ldsw + _i * 8192), 16, 0, 0); } while (0)
; #define PG8_LDA(dst, b, h) do { _Pragma("unroll") for (int m = 0; m < 4; ++m) _Pragma("unroll") for (int k = 0; k < 2; ++k) dst[m][k] = *(const LAS bf16x8*)(lds + PG8_SA(b, h) + aoff + m * 2048 + k * 1024); } while (0)
; #define PG8_LDB(dst, b, h) do { _Pragma("unroll") for (int n = 0; n < 2; ++n) _Pragma("unroll") for (int k = 0; k < 2; ++k) dst[n][k] = *(const LAS bf16x8*)(lds + PG8_SB(b, h) + boff + n * 2048 + k * 1024); } while (0)
; #define PG8_MMA(ai, bj, At, Bt) do { __builtin_amdgcn_s_setprio(1); _Pragma("unroll") for (int m = 0; m < 4; ++m) _Pragma("unroll") for (int n = 0; n < 2; ++n) _Pragma("unroll") for (int k = 0; k < 2; ++k) \
;         acc[ai][bj][m][n] = __builtin_amdgcn_mfma_f32_16x16x32_bf16(Bt[n][k], At[m][k], acc[ai][bj][m][n], 0, 0, 0); __builtin_amdgcn_s_setprio(0); } while (0)
; #define PG8_WAIT_V(n) asm volatile("s_waitcnt vmcnt(" #n ")" ::: "memory")
; #define PG8_WAIT_L(n) asm volatile("s_waitcnt lgkmcnt(" #n ")" ::: "memory")
; #define PG8_BAR __builtin_amdgcn_s_barrier()
; #define PG8_SCHED __builtin_amdgcn_sched_barrier(0)
; template <class Epi, class Sched>
; DI void gemm_phase(LAS unsigned char* lds, const Gemm g, const Sched& S, const Epi& E) {
;     ...
;             PG8_WAIT_V(6); PG8_BAR; PG8_MMA(1, 1, At, B1); PG8_BAR;
;             PG8_LDB(B0, 1, 0); PG8_SCHED; PG8_LDA(At, 1, 0); PG8_STAGE(PG8_SA(0, 1), a2 + hstep, voffA);
;             PG8_WAIT_L(8); PG8_BAR; PG8_WAIT_L(0); PG8_MMA(0, 0, At, B0); PG8_BAR; PG8_SCHED;
;             PG8_LDB(B1, 1, 1); PG8_STAGE(PG8_SB(1, 0), b3, voffB);
;             PG8_BAR; PG8_WAIT_L(0); PG8_MMA(0, 1, At, B1); PG8_BAR;
;             PG8_LDA(At, 1, 1); PG8_STAGE(PG8_SA(1, 0), a3, voffA);
;             PG8_BAR; PG8_WAIT_L(0); PG8_MMA(1, 0, At, B0); PG8_BAR; PG8_SCHED;
;             PG8_STAGE(PG8_SB(1, 1), b3 + hstep, voffB);
;             PG8_WAIT_V(6); PG8_BAR; PG8_MMA(1, 1, At, B1); PG8_BAR;
	s_add_u32 s72, s24, 0x40000
	s_addc_u32 s73, s25, 0
	s_add_i32 s67, s35, s12
	v_lshl_add_u64 v[140:141], s[72:73], 0, v[132:133]
	s_mov_b32 m0, s67
	s_nop 0
	global_load_lds_dwordx4 v[140:141], off
	v_lshl_add_u64 v[140:141], s[72:73], 0, v[130:131]
	s_add_i32 m0, s67, 0x2000
	s_nop 0
	global_load_lds_dwordx4 v[140:141], off
	s_waitcnt vmcnt(6)
	s_barrier
	s_setprio 1
	v_mfma_f32_16x16x32_bf16 v[54:57], v[202:205], v[168:171], v[54:57]
	v_mfma_f32_16x16x32_bf16 v[46:49], v[210:213], v[168:171], v[46:49]
	v_mfma_f32_16x16x32_bf16 v[38:41], v[202:205], v[176:179], v[38:41]
	v_mfma_f32_16x16x32_bf16 v[30:33], v[210:213], v[176:179], v[30:33]
	v_mfma_f32_16x16x32_bf16 v[22:25], v[202:205], v[184:187], v[22:25]
	v_mfma_f32_16x16x32_bf16 v[14:17], v[210:213], v[184:187], v[14:17]
	v_mfma_f32_16x16x32_bf16 v[6:9], v[202:205], v[192:195], v[6:9]
	v_mfma_f32_16x16x32_bf16 v[2:5], v[210:213], v[192:195], v[2:5]
	v_mfma_f32_16x16x32_bf16 v[54:57], v[206:209], v[172:175], v[54:57]
	v_mfma_f32_16x16x32_bf16 v[46:49], v[214:217], v[172:175], v[46:49]
	v_mfma_f32_16x16x32_bf16 v[38:41], v[206:209], v[180:183], v[38:41]
	v_mfma_f32_16x16x32_bf16 v[30:33], v[214:217], v[180:183], v[30:33]
	v_mfma_f32_16x16x32_bf16 v[22:25], v[206:209], v[188:191], v[22:25]
	v_mfma_f32_16x16x32_bf16 v[14:17], v[214:217], v[188:191], v[14:17]
	v_mfma_f32_16x16x32_bf16 v[6:9], v[206:209], v[198:201], v[6:9]
	v_mfma_f32_16x16x32_bf16 v[2:5], v[214:217], v[198:201], v[2:5]
	s_setprio 0
	s_add_i32 s67, 0, 0x18000
	v_add_u32_e32 v134, s67, v145
	s_barrier
	ds_read_b128 v[140:143], v134
	ds_read_b128 v[154:157], v134 offset:1024
	ds_read_b128 v[158:161], v134 offset:2048
	ds_read_b128 v[164:167], v134 offset:3072
	s_add_u32 s26, s26, 0x40000
	s_addc_u32 s27, s27, 0
	s_mov_b32 m0, s29
	v_lshl_add_u64 v[202:203], s[26:27], 0, v[132:133]
	ds_read_b128 v[168:171], v148 offset:32768
	ds_read_b128 v[172:175], v148 offset:33792
	ds_read_b128 v[176:179], v148 offset:34816
	ds_read_b128 v[180:183], v148 offset:35840
	ds_read_b128 v[184:187], v148 offset:36864
	ds_read_b128 v[188:191], v148 offset:37888
	ds_read_b128 v[192:195], v148 offset:38912
	ds_read_b128 v[198:201], v148 offset:39936
	global_load_lds_dwordx4 v[202:203], off
	v_lshl_add_u64 v[202:203], s[26:27], 0, v[130:131]
	s_mov_b32 m0, s30
	s_nop 0
	global_load_lds_dwordx4 v[202:203], off
	s_waitcnt lgkmcnt(8)
	s_barrier
	s_waitcnt lgkmcnt(0)
	s_setprio 1
	s_waitcnt lgkmcnt(0)
	v_mfma_f32_16x16x32_bf16 v[126:129], v[140:143], v[168:171], v[126:129]
	v_mfma_f32_16x16x32_bf16 v[122:125], v[158:161], v[168:171], v[122:125]
	v_mfma_f32_16x16x32_bf16 v[114:117], v[140:143], v[176:179], v[114:117]
	v_mfma_f32_16x16x32_bf16 v[106:109], v[158:161], v[176:179], v[106:109]
	v_mfma_f32_16x16x32_bf16 v[98:101], v[140:143], v[184:187], v[98:101]
	v_mfma_f32_16x16x32_bf16 v[90:93], v[158:161], v[184:187], v[90:93]
	v_mfma_f32_16x16x32_bf16 v[82:85], v[140:143], v[192:195], v[82:85]
	v_mfma_f32_16x16x32_bf16 v[74:77], v[158:161], v[192:195], v[74:77]
	v_mfma_f32_16x16x32_bf16 v[126:129], v[154:157], v[172:175], v[126:129]
	v_mfma_f32_16x16x32_bf16 v[122:125], v[164:167], v[172:175], v[122:125]
	v_mfma_f32_16x16x32_bf16 v[114:117], v[154:157], v[180:183], v[114:117]
	v_mfma_f32_16x16x32_bf16 v[106:109], v[164:167], v[180:183], v[106:109]
	v_mfma_f32_16x16x32_bf16 v[98:101], v[154:157], v[188:191], v[98:101]
	v_mfma_f32_16x16x32_bf16 v[90:93], v[164:167], v[188:191], v[90:93]
	v_mfma_f32_16x16x32_bf16 v[82:85], v[154:157], v[198:201], v[82:85]
	v_mfma_f32_16x16x32_bf16 v[74:77], v[164:167], v[198:201], v[74:77]
	s_setprio 0
	s_barrier
	s_add_i32 s26, 0, 0x1c000
	s_add_i32 s27, s67, s12
	v_add_u32_e32 v134, s26, v145
	v_lshl_add_u64 v[150:151], v[150:151], 0, s[10:11]
	s_mov_b32 m0, s27
	ds_read_b128 v[202:205], v134
	ds_read_b128 v[206:209], v134 offset:1024
	ds_read_b128 v[210:213], v134 offset:2048
	ds_read_b128 v[214:217], v134 offset:3072
	global_load_lds_dwordx4 v[150:151], off
	v_lshl_add_u64 v[150:151], v[218:219], 0, s[10:11]
	s_add_i32 m0, s27, 0x2000
	s_nop 0
	global_load_lds_dwordx4 v[150:151], off
	s_barrier
	s_waitcnt lgkmcnt(0)
	s_setprio 1
	s_waitcnt lgkmcnt(0)
	v_mfma_f32_16x16x32_bf16 v[118:121], v[202:205], v[168:171], v[118:121]
	v_mfma_f32_16x16x32_bf16 v[110:113], v[210:213], v[168:171], v[110:113]
	v_mfma_f32_16x16x32_bf16 v[102:105], v[202:205], v[176:179], v[102:105]
	v_mfma_f32_16x16x32_bf16 v[94:97], v[210:213], v[176:179], v[94:97]
	v_mfma_f32_16x16x32_bf16 v[86:89], v[202:205], v[184:187], v[86:89]
	v_mfma_f32_16x16x32_bf16 v[78:81], v[210:213], v[184:187], v[78:81]
	v_mfma_f32_16x16x32_bf16 v[70:73], v[202:205], v[192:195], v[70:73]
	v_mfma_f32_16x16x32_bf16 v[66:69], v[210:213], v[192:195], v[66:69]
	v_mfma_f32_16x16x32_bf16 v[118:121], v[206:209], v[172:175], v[118:121]
	v_mfma_f32_16x16x32_bf16 v[110:113], v[214:217], v[172:175], v[110:113]
	v_mfma_f32_16x16x32_bf16 v[102:105], v[206:209], v[180:183], v[102:105]
	v_mfma_f32_16x16x32_bf16 v[94:97], v[214:217], v[180:183], v[94:97]
	v_mfma_f32_16x16x32_bf16 v[86:89], v[206:209], v[188:191], v[86:89]
	v_mfma_f32_16x16x32_bf16 v[78:81], v[214:217], v[188:191], v[78:81]
	v_mfma_f32_16x16x32_bf16 v[70:73], v[206:209], v[198:201], v[70:73]
	v_mfma_f32_16x16x32_bf16 v[66:69], v[214:217], v[198:201], v[66:69]
	s_setprio 0
	s_mov_b32 m0, s33
	v_lshl_add_u64 v[150:151], v[220:221], 0, s[10:11]
	s_barrier
	ds_read_b128 v[168:171], v148 offset:49152
	ds_read_b128 v[172:175], v148 offset:50176
	ds_read_b128 v[176:179], v148 offset:51200
	ds_read_b128 v[180:183], v148 offset:52224
	ds_read_b128 v[184:187], v148 offset:53248
	ds_read_b128 v[188:191], v148 offset:54272
	ds_read_b128 v[192:195], v148 offset:55296
	ds_read_b128 v[198:201], v148 offset:56320
	global_load_lds_dwordx4 v[150:151], off
	v_lshl_add_u64 v[150:151], v[222:223], 0, s[10:11]
	s_mov_b32 m0, s34
	s_nop 0
	global_load_lds_dwordx4 v[150:151], off
	s_barrier
; DI unsigned pk_bf16(float a, float b) { f32x2 v = {a, b}; bf2_t r = __builtin_convertvector(v, bf2_t); return __builtin_bit_cast(unsigned, r); }
; DI float bflo(unsigned u) { return __uint_as_float(u << 16); }
; DI float bfhi(unsigned u) { return __uint_as_float(u & 0xffff0000u); }
; #define PG8_STAGE(bufoff, gbase, voff) do { _Pragma("unroll") for (int _i = 0; _i < 2; ++_i) \
;         __builtin_amdgcn_global_load_lds((const unsigned*)((const char*)(gbase) + (voff)[_i]), (LAS unsigned*)(lds + (bufoff) + ldsw + _i * 8192), 16, 0, 0); } while (0)
; #define PG8_MMA(ai, bj, At, Bt) do { __builtin_amdgcn_s_setprio(1); _Pragma("unroll") for (int m = 0; m < 4; ++m) _Pragma("unroll") for (int n = 0; n < 2; ++n) _Pragma("unroll") for (int k = 0; k < 2; ++k) \
;         acc[ai][bj][m][n] = __builtin_amdgcn_mfma_f32_16x16x32_bf16(Bt[n][k], At[m][k], acc[ai][bj][m][n], 0, 0, 0); __builtin_amdgcn_s_setprio(0); } while (0)
; #define PG8_WAIT_V(n) asm volatile("s_waitcnt vmcnt(" #n ")" ::: "memory")
; #define PG8_BAR __builtin_amdgcn_s_barrier()
;     DI void operator()(const f32x4 (&acc)[2][2][4][2], const Unit& u, int wr, int wc, int fr, int fq) const {
;         const int row0 = u.pm * BM + wr * 64 + fr, col0 = u.pn * BM + wc * 32 + 4 * fq;
; #pragma unroll
;         for (int ai = 0; ai < 2; ++ai)
; #pragma unroll
;             for (int m = 0; m < 4; ++m) { const size_t o = (size_t)(row0 + ai * HALF + m * 16) * 1024 + col0;
; #pragma unroll
;                 for (int bj = 0; bj < 2; ++bj)
; #pragma unroll
;                     for (int n = 0; n < 2; ++n) { const size_t oo = o + bj * HALF + n * 16; f32x4 rv;
;                         if (RES_BF16) { const u32x2 t = *(const u32x2*)((const bf16_t*)res + oo); rv = (f32x4){bflo(t.x), bfhi(t.x), bflo(t.y), bfhi(t.y)}; }
;                         else rv = *(const f32x4*)((const float*)res + oo);
;                         const f32x4 v = acc[ai][bj][m][n] + rv; u32x2 w; w.x = pk_bf16(v.x, v.y); w.y = pk_bf16(v.z, v.w);
;                         *(u32x2*)(O + oo) = w; } }
; template <class Epi, class Sched>
; DI void gemm_phase(LAS unsigned char* lds, const Gemm g, const Sched& S, const Epi& E) {
;     ...
;             PG8_BAR; PG8_WAIT_L(0); PG8_MMA(1, 0, At, B0); PG8_BAR; PG8_SCHED;
;             PG8_STAGE(PG8_SB(1, 1), b3 + hstep, voffB);
;             PG8_WAIT_V(6); PG8_BAR; PG8_MMA(1, 1, At, B1); PG8_BAR;
	s_waitcnt lgkmcnt(0)
	s_setprio 1
	s_waitcnt lgkmcnt(0)
	v_mfma_f32_16x16x32_bf16 v[62:65], v[140:143], v[168:171], v[62:65]
	v_mfma_f32_16x16x32_bf16 v[58:61], v[158:161], v[168:171], v[58:61]
	v_mfma_f32_16x16x32_bf16 v[50:53], v[140:143], v[176:179], v[50:53]
	v_mfma_f32_16x16x32_bf16 v[42:45], v[158:161], v[176:179], v[42:45]
	v_mfma_f32_16x16x32_bf16 v[34:37], v[140:143], v[184:187], v[34:37]
	v_mfma_f32_16x16x32_bf16 v[26:29], v[158:161], v[184:187], v[26:29]
	v_mfma_f32_16x16x32_bf16 v[18:21], v[140:143], v[192:195], v[18:21]
	v_mfma_f32_16x16x32_bf16 v[10:13], v[158:161], v[192:195], v[10:13]
	v_mfma_f32_16x16x32_bf16 v[62:65], v[154:157], v[172:175], v[62:65]
	v_mfma_f32_16x16x32_bf16 v[58:61], v[164:167], v[172:175], v[58:61]
	v_mfma_f32_16x16x32_bf16 v[50:53], v[154:157], v[180:183], v[50:53]
	v_mfma_f32_16x16x32_bf16 v[42:45], v[164:167], v[180:183], v[42:45]
	v_mfma_f32_16x16x32_bf16 v[34:37], v[154:157], v[188:191], v[34:37]
	v_mfma_f32_16x16x32_bf16 v[26:29], v[164:167], v[188:191], v[26:29]
	v_mfma_f32_16x16x32_bf16 v[18:21], v[154:157], v[198:201], v[18:21]
	v_mfma_f32_16x16x32_bf16 v[10:13], v[164:167], v[198:201], v[10:13]
	s_setprio 0
	s_barrier
	s_add_u32 s24, s24, 0x40080
	s_addc_u32 s25, s25, 0
	s_add_i32 s26, s26, s12
	v_lshl_add_u64 v[140:141], s[24:25], 0, v[132:133]
	s_mov_b32 m0, s26
	s_nop 0
	global_load_lds_dwordx4 v[140:141], off
	v_lshl_add_u64 v[140:141], s[24:25], 0, v[130:131]
	s_add_i32 m0, s26, 0x2000
	s_nop 0
	global_load_lds_dwordx4 v[140:141], off
	s_waitcnt vmcnt(6)
	s_barrier
	s_setprio 1
	v_mfma_f32_16x16x32_bf16 v[54:57], v[202:205], v[168:171], v[54:57]
	v_mfma_f32_16x16x32_bf16 v[46:49], v[210:213], v[168:171], v[46:49]
	v_mfma_f32_16x16x32_bf16 v[38:41], v[202:205], v[176:179], v[38:41]
	v_mfma_f32_16x16x32_bf16 v[30:33], v[210:213], v[176:179], v[30:33]
	v_mfma_f32_16x16x32_bf16 v[22:25], v[202:205], v[184:187], v[22:25]
	v_mfma_f32_16x16x32_bf16 v[14:17], v[210:213], v[184:187], v[14:17]
	v_mfma_f32_16x16x32_bf16 v[6:9], v[202:205], v[192:195], v[6:9]
	v_mfma_f32_16x16x32_bf16 v[2:5], v[210:213], v[192:195], v[2:5]
	v_mfma_f32_16x16x32_bf16 v[54:57], v[206:209], v[172:175], v[54:57]
	v_mfma_f32_16x16x32_bf16 v[46:49], v[214:217], v[172:175], v[46:49]
	v_mfma_f32_16x16x32_bf16 v[38:41], v[206:209], v[180:183], v[38:41]
	v_mfma_f32_16x16x32_bf16 v[30:33], v[214:217], v[180:183], v[30:33]
	v_mfma_f32_16x16x32_bf16 v[22:25], v[206:209], v[188:191], v[22:25]
	v_mfma_f32_16x16x32_bf16 v[14:17], v[214:217], v[188:191], v[14:17]
	v_mfma_f32_16x16x32_bf16 v[6:9], v[206:209], v[198:201], v[6:9]
	v_mfma_f32_16x16x32_bf16 v[2:5], v[214:217], v[198:201], v[2:5]
	s_setprio 0
	s_add_i32 s66, s66, 2
	s_add_u32 s22, s22, 0x100
	s_addc_u32 s23, s23, 0
	s_add_u32 s58, s58, 0x100
	s_addc_u32 s59, s59, 0
	s_cmp_gt_u32 s66, 13
	s_barrier
	s_cbranch_scc0 .LBB0_1007
	v_lshl_add_u32 v224, s43, 8, v144
	v_lshl_or_b32 v242, s42, 8, v146
	v_lshl_or_b32 v224, v224, 10, v242
	s_and_b64 vcc, exec, s[20:21]
	s_mov_b32 s42, s40
	s_mov_b32 s43, s41
	s_mov_b64 s[22:23], 0x2c000
	v_lshlrev_b32_e32 v225, 2, v224
	v_lshlrev_b32_e32 v233, 1, v224
	v_add_u32_e32 v234, 0x4000, v224
	v_lshlrev_b32_e32 v226, 2, v234
	v_lshlrev_b32_e32 v234, 1, v234
	v_add_u32_e32 v235, 0x8000, v224
	v_lshlrev_b32_e32 v227, 2, v235
	v_lshlrev_b32_e32 v235, 1, v235
	v_add_u32_e32 v236, 0xc000, v224
	v_lshlrev_b32_e32 v228, 2, v236
	v_lshlrev_b32_e32 v236, 1, v236
	v_add_u32_e32 v237, 0x20000, v224
	v_lshlrev_b32_e32 v229, 2, v237
	v_lshlrev_b32_e32 v237, 1, v237
	v_add_u32_e32 v239, 0x24000, v224
	v_lshlrev_b32_e32 v230, 2, v239
	v_lshlrev_b32_e32 v239, 1, v239
	v_add_u32_e32 v240, 0x28000, v224
	v_lshlrev_b32_e32 v231, 2, v240
	v_lshlrev_b32_e32 v240, 1, v240
	v_add_u32_e32 v241, 0x2c000, v224
	v_lshlrev_b32_e32 v232, 2, v241
	v_lshlrev_b32_e32 v241, 1, v241
	global_load_dwordx4 v[140:143], v225, s[60:61]
	global_load_dwordx4 v[154:157], v225, s[60:61] offset:64
	global_load_dwordx4 v[158:161], v225, s[60:61] offset:512
	global_load_dwordx4 v[164:167], v225, s[60:61] offset:576
	global_load_dwordx4 v[168:171], v226, s[60:61]
	global_load_dwordx4 v[172:175], v226, s[60:61] offset:64
	global_load_dwordx4 v[176:179], v226, s[60:61] offset:512
	global_load_dwordx4 v[180:183], v226, s[60:61] offset:576
	global_load_dwordx4 v[184:187], v227, s[60:61]
	global_load_dwordx4 v[188:191], v227, s[60:61] offset:64
	global_load_dwordx4 v[192:195], v227, s[60:61] offset:512
	global_load_dwordx4 v[198:201], v227, s[60:61] offset:576
	global_load_dwordx4 v[202:205], v228, s[60:61]
	global_load_dwordx4 v[206:209], v228, s[60:61] offset:64
	global_load_dwordx4 v[210:213], v228, s[60:61] offset:512
	global_load_dwordx4 v[214:217], v228, s[60:61] offset:576
	s_waitcnt vmcnt(12)
	v_pk_add_f32 v[128:129], v[128:129], v[142:143]
	v_pk_add_f32 v[126:127], v[126:127], v[140:141]
	v_pk_add_f32 v[124:125], v[124:125], v[156:157]
	v_pk_add_f32 v[122:123], v[122:123], v[154:155]
	v_pk_add_f32 v[120:121], v[120:121], v[160:161]
	v_pk_add_f32 v[118:119], v[118:119], v[158:159]
	v_pk_add_f32 v[112:113], v[112:113], v[166:167]
	v_pk_add_f32 v[110:111], v[110:111], v[164:165]
	v_cvt_pk_bf16_f32 v126, v126, v127
	v_cvt_pk_bf16_f32 v127, v128, v129
	v_cvt_pk_bf16_f32 v122, v122, v123
	v_cvt_pk_bf16_f32 v123, v124, v125
	v_cvt_pk_bf16_f32 v118, v118, v119
	v_cvt_pk_bf16_f32 v119, v120, v121
	v_cvt_pk_bf16_f32 v110, v110, v111
	v_cvt_pk_bf16_f32 v111, v112, v113
	global_store_dwordx2 v233, v[126:127], s[48:49]
	global_store_dwordx2 v233, v[122:123], s[48:49] offset:32
	global_store_dwordx2 v233, v[118:119], s[48:49] offset:256
	global_store_dwordx2 v233, v[110:111], s[48:49] offset:288
	global_load_dwordx4 v[140:143], v229, s[60:61]
	global_load_dwordx4 v[154:157], v229, s[60:61] offset:64
	global_load_dwordx4 v[158:161], v229, s[60:61] offset:512
	global_load_dwordx4 v[164:167], v229, s[60:61] offset:576
	s_waitcnt vmcnt(16)
; DI unsigned pk_bf16(float a, float b) { f32x2 v = {a, b}; bf2_t r = __builtin_convertvector(v, bf2_t); return __builtin_bit_cast(unsigned, r); }
; DI float bflo(unsigned u) { return __uint_as_float(u << 16); }
; DI float bfhi(unsigned u) { return __uint_as_float(u & 0xffff0000u); }
;     DI void operator()(const f32x4 (&acc)[2][2][4][2], const Unit& u, int wr, int wc, int fr, int fq) const {
;     ...
;             for (int m = 0; m < 4; ++m) { const size_t o = (size_t)(row0 + ai * HALF + m * 16) * 1024 + col0;
; #pragma unroll
;                 for (int bj = 0; bj < 2; ++bj)
; #pragma unroll
;                     for (int n = 0; n < 2; ++n) { const size_t oo = o + bj * HALF + n * 16; f32x4 rv;
;                         if (RES_BF16) { const u32x2 t = *(const u32x2*)((const bf16_t*)res + oo); rv = (f32x4){bflo(t.x), bfhi(t.x), bflo(t.y), bfhi(t.y)}; }
;                         else rv = *(const f32x4*)((const float*)res + oo);
;                         const f32x4 v = acc[ai][bj][m][n] + rv; u32x2 w; w.x = pk_bf16(v.x, v.y); w.y = pk_bf16(v.z, v.w);
;                         *(u32x2*)(O + oo) = w; } }
	v_pk_add_f32 v[116:117], v[116:117], v[170:171]
	v_pk_add_f32 v[114:115], v[114:115], v[168:169]
	v_pk_add_f32 v[108:109], v[108:109], v[174:175]
	v_pk_add_f32 v[106:107], v[106:107], v[172:173]
	v_pk_add_f32 v[104:105], v[104:105], v[178:179]
	v_pk_add_f32 v[102:103], v[102:103], v[176:177]
	v_pk_add_f32 v[96:97], v[96:97], v[182:183]
	v_pk_add_f32 v[94:95], v[94:95], v[180:181]
	v_cvt_pk_bf16_f32 v114, v114, v115
	v_cvt_pk_bf16_f32 v115, v116, v117
	v_cvt_pk_bf16_f32 v106, v106, v107
	v_cvt_pk_bf16_f32 v107, v108, v109
	v_cvt_pk_bf16_f32 v102, v102, v103
	v_cvt_pk_bf16_f32 v103, v104, v105
	v_cvt_pk_bf16_f32 v94, v94, v95
	v_cvt_pk_bf16_f32 v95, v96, v97
	global_store_dwordx2 v234, v[114:115], s[48:49]
	global_store_dwordx2 v234, v[106:107], s[48:49] offset:32
	global_store_dwordx2 v234, v[102:103], s[48:49] offset:256
	global_store_dwordx2 v234, v[94:95], s[48:49] offset:288
	global_load_dwordx4 v[168:171], v230, s[60:61]
	global_load_dwordx4 v[172:175], v230, s[60:61] offset:64
	global_load_dwordx4 v[176:179], v230, s[60:61] offset:512
	global_load_dwordx4 v[180:183], v230, s[60:61] offset:576
	s_waitcnt vmcnt(20)
	v_pk_add_f32 v[100:101], v[100:101], v[186:187]
	v_pk_add_f32 v[98:99], v[98:99], v[184:185]
	v_pk_add_f32 v[92:93], v[92:93], v[190:191]
	v_pk_add_f32 v[90:91], v[90:91], v[188:189]
	v_pk_add_f32 v[88:89], v[88:89], v[194:195]
	v_pk_add_f32 v[86:87], v[86:87], v[192:193]
	v_pk_add_f32 v[80:81], v[80:81], v[200:201]
	v_pk_add_f32 v[78:79], v[78:79], v[198:199]
	v_cvt_pk_bf16_f32 v98, v98, v99
	v_cvt_pk_bf16_f32 v99, v100, v101
	v_cvt_pk_bf16_f32 v90, v90, v91
	v_cvt_pk_bf16_f32 v91, v92, v93
	v_cvt_pk_bf16_f32 v86, v86, v87
	v_cvt_pk_bf16_f32 v87, v88, v89
	v_cvt_pk_bf16_f32 v78, v78, v79
	v_cvt_pk_bf16_f32 v79, v80, v81
	global_store_dwordx2 v235, v[98:99], s[48:49]
	global_store_dwordx2 v235, v[90:91], s[48:49] offset:32
	global_store_dwordx2 v235, v[86:87], s[48:49] offset:256
	global_store_dwordx2 v235, v[78:79], s[48:49] offset:288
	global_load_dwordx4 v[184:187], v231, s[60:61]
	global_load_dwordx4 v[188:191], v231, s[60:61] offset:64
	global_load_dwordx4 v[192:195], v231, s[60:61] offset:512
	global_load_dwordx4 v[198:201], v231, s[60:61] offset:576
	s_waitcnt vmcnt(24)
	v_pk_add_f32 v[84:85], v[84:85], v[204:205]
	v_pk_add_f32 v[82:83], v[82:83], v[202:203]
	v_pk_add_f32 v[76:77], v[76:77], v[208:209]
	v_pk_add_f32 v[74:75], v[74:75], v[206:207]
	v_pk_add_f32 v[72:73], v[72:73], v[212:213]
	v_pk_add_f32 v[70:71], v[70:71], v[210:211]
	v_pk_add_f32 v[68:69], v[68:69], v[216:217]
	v_pk_add_f32 v[66:67], v[66:67], v[214:215]
	v_cvt_pk_bf16_f32 v82, v82, v83
	v_cvt_pk_bf16_f32 v83, v84, v85
	v_cvt_pk_bf16_f32 v74, v74, v75
	v_cvt_pk_bf16_f32 v75, v76, v77
	v_cvt_pk_bf16_f32 v70, v70, v71
	v_cvt_pk_bf16_f32 v71, v72, v73
	v_cvt_pk_bf16_f32 v66, v66, v67
	v_cvt_pk_bf16_f32 v67, v68, v69
	global_store_dwordx2 v236, v[82:83], s[48:49]
	global_store_dwordx2 v236, v[74:75], s[48:49] offset:32
	global_store_dwordx2 v236, v[70:71], s[48:49] offset:256
	global_store_dwordx2 v236, v[66:67], s[48:49] offset:288
	global_load_dwordx4 v[202:205], v232, s[60:61]
	global_load_dwordx4 v[206:209], v232, s[60:61] offset:64
	global_load_dwordx4 v[210:213], v232, s[60:61] offset:512
	global_load_dwordx4 v[214:217], v232, s[60:61] offset:576
	s_waitcnt vmcnt(24)
	v_pk_add_f32 v[64:65], v[64:65], v[142:143]
	v_pk_add_f32 v[62:63], v[62:63], v[140:141]
	v_pk_add_f32 v[60:61], v[60:61], v[156:157]
	v_pk_add_f32 v[58:59], v[58:59], v[154:155]
	v_pk_add_f32 v[56:57], v[56:57], v[160:161]
	v_pk_add_f32 v[54:55], v[54:55], v[158:159]
	v_pk_add_f32 v[48:49], v[48:49], v[166:167]
	v_pk_add_f32 v[46:47], v[46:47], v[164:165]
	v_cvt_pk_bf16_f32 v62, v62, v63
	v_cvt_pk_bf16_f32 v63, v64, v65
	v_cvt_pk_bf16_f32 v58, v58, v59
	v_cvt_pk_bf16_f32 v59, v60, v61
	v_cvt_pk_bf16_f32 v54, v54, v55
	v_cvt_pk_bf16_f32 v55, v56, v57
	v_cvt_pk_bf16_f32 v46, v46, v47
	v_cvt_pk_bf16_f32 v47, v48, v49
	global_store_dwordx2 v237, v[62:63], s[48:49]
	global_store_dwordx2 v237, v[58:59], s[48:49] offset:32
	global_store_dwordx2 v237, v[54:55], s[48:49] offset:256
	global_store_dwordx2 v237, v[46:47], s[48:49] offset:288
	s_waitcnt vmcnt(20)
	v_pk_add_f32 v[52:53], v[52:53], v[170:171]
	v_pk_add_f32 v[50:51], v[50:51], v[168:169]
	v_pk_add_f32 v[44:45], v[44:45], v[174:175]
	v_pk_add_f32 v[42:43], v[42:43], v[172:173]
	v_pk_add_f32 v[40:41], v[40:41], v[178:179]
	v_pk_add_f32 v[38:39], v[38:39], v[176:177]
	v_pk_add_f32 v[32:33], v[32:33], v[182:183]
	v_pk_add_f32 v[30:31], v[30:31], v[180:181]
	v_cvt_pk_bf16_f32 v50, v50, v51
	v_cvt_pk_bf16_f32 v51, v52, v53
	v_cvt_pk_bf16_f32 v42, v42, v43
	v_cvt_pk_bf16_f32 v43, v44, v45
	v_cvt_pk_bf16_f32 v38, v38, v39
	v_cvt_pk_bf16_f32 v39, v40, v41
	v_cvt_pk_bf16_f32 v30, v30, v31
	v_cvt_pk_bf16_f32 v31, v32, v33
	global_store_dwordx2 v239, v[50:51], s[48:49]
	global_store_dwordx2 v239, v[42:43], s[48:49] offset:32
	global_store_dwordx2 v239, v[38:39], s[48:49] offset:256
	global_store_dwordx2 v239, v[30:31], s[48:49] offset:288
	s_waitcnt vmcnt(16)
	v_pk_add_f32 v[36:37], v[36:37], v[186:187]
	v_pk_add_f32 v[34:35], v[34:35], v[184:185]
	v_pk_add_f32 v[28:29], v[28:29], v[190:191]
	v_pk_add_f32 v[26:27], v[26:27], v[188:189]
	v_pk_add_f32 v[24:25], v[24:25], v[194:195]
	v_pk_add_f32 v[22:23], v[22:23], v[192:193]
	v_pk_add_f32 v[16:17], v[16:17], v[200:201]
	v_pk_add_f32 v[14:15], v[14:15], v[198:199]
	v_cvt_pk_bf16_f32 v34, v34, v35
	v_cvt_pk_bf16_f32 v35, v36, v37
	v_cvt_pk_bf16_f32 v26, v26, v27
	v_cvt_pk_bf16_f32 v27, v28, v29
	v_cvt_pk_bf16_f32 v22, v22, v23
	v_cvt_pk_bf16_f32 v23, v24, v25
	v_cvt_pk_bf16_f32 v14, v14, v15
	v_cvt_pk_bf16_f32 v15, v16, v17
	global_store_dwordx2 v240, v[34:35], s[48:49]
	global_store_dwordx2 v240, v[26:27], s[48:49] offset:32
	global_store_dwordx2 v240, v[22:23], s[48:49] offset:256
	global_store_dwordx2 v240, v[14:15], s[48:49] offset:288
	s_waitcnt vmcnt(12)
	v_pk_add_f32 v[20:21], v[20:21], v[204:205]
	v_pk_add_f32 v[18:19], v[18:19], v[202:203]
	v_pk_add_f32 v[12:13], v[12:13], v[208:209]
	v_pk_add_f32 v[10:11], v[10:11], v[206:207]
	v_pk_add_f32 v[8:9], v[8:9], v[212:213]
	v_pk_add_f32 v[6:7], v[6:7], v[210:211]
	v_pk_add_f32 v[4:5], v[4:5], v[216:217]
	v_pk_add_f32 v[2:3], v[2:3], v[214:215]
	v_cvt_pk_bf16_f32 v18, v18, v19
	v_cvt_pk_bf16_f32 v19, v20, v21
	v_cvt_pk_bf16_f32 v10, v10, v11
	v_cvt_pk_bf16_f32 v11, v12, v13
	v_cvt_pk_bf16_f32 v6, v6, v7
	v_cvt_pk_bf16_f32 v7, v8, v9
	v_cvt_pk_bf16_f32 v2, v2, v3
	v_cvt_pk_bf16_f32 v3, v4, v5
	global_store_dwordx2 v241, v[18:19], s[48:49]
	global_store_dwordx2 v241, v[10:11], s[48:49] offset:32
	global_store_dwordx2 v241, v[6:7], s[48:49] offset:256
	global_store_dwordx2 v241, v[2:3], s[48:49] offset:288
	s_cbranch_vccz .LBB0_1006
	s_waitcnt vmcnt(0)
	s_cmpk_gt_u32 s3, 0xff
	s_cbranch_scc1 .LBB0_1011
	s_barrier

; DI float bflo(unsigned u) { return __uint_as_float(u << 16); }
; DI float bfhi(unsigned u) { return __uint_as_float(u & 0xffff0000u); }
; DI void phase_norm1(const Params& p) {
;     const int lane = threadIdx.x & 63, gw = blockIdx.x * 8 + (threadIdx.x >> 6), nw = gridDim.x * 8;
;     bf16_t* x1 = (bf16_t*)(p.ws + WS_X1); const float* part = (const float*)(p.ws + WS_PART1); bf16_t* out = (bf16_t*)(p.ws + WS_XN); const float* w = p.norm_w + 1024;
;     for (int tok = gw; tok < T_TOK; tok += nw) {
;         f32x4 v[4]; float ss = 0.f;
; #pragma unroll
;         for (int i = 0; i < 4; ++i) { const int c = 4 * lane + 256 * i;
;             if (tok < T_PR) { const u32x2 t = *(const u32x2*)(x1 + (size_t)tok * 1024 + c); v[i] = (f32x4){bflo(t.x), bfhi(t.x), bflo(t.y), bfhi(t.y)}; }
.LBB0_1095:
	s_cmp_lt_i32 s80, 7
	s_cselect_b64 s[6:7], -1, 0
	s_and_b64 s[0:1], s[6:7], s[0:1]
	s_and_b64 s[0:1], s[44:45], s[0:1]
	v_lshlrev_b32_e32 v164, 2, v152
	v_lshlrev_b32_e32 v166, 1, v152
	s_and_saveexec_b64 s[8:9], s[0:1]
	s_cbranch_execz .LBB0_1114
	v_lshlrev_b32_e32 v2, 3, v196
	v_lshlrev_b32_e32 v3, 4, v196
	s_add_u32 s10, s70, 0x1000
	s_addc_u32 s11, s71, 0
	s_add_u32 s12, s78, 0xc480000
	s_addc_u32 s13, s79, 0
	s_add_u32 s16, s78, 0x1a80000
	s_addc_u32 s17, s79, 0
	global_load_dwordx4 v[16:19], v3, s[10:11]
	global_load_dwordx4 v[20:23], v3, s[10:11] offset:1024
	global_load_dwordx4 v[24:27], v3, s[10:11] offset:2048
	global_load_dwordx4 v[28:31], v3, s[10:11] offset:3072
	v_readfirstlane_b32 s4, v162
	s_mov_b32 s23, 0
	v_mov_b32_e32 v60, 0x358637bd
	s_cmp_lt_u32 s4, 0x4000
	s_cbranch_scc0 .Ln1_sample
	s_lshl_b32 s5, s4, 11
	v_add_u32_e32 v4, s5, v2
	global_load_dwordx2 v[32:33], v4, s[12:13]
	global_load_dwordx2 v[34:35], v4, s[12:13] offset:512
	global_load_dwordx2 v[36:37], v4, s[12:13] offset:1024
	global_load_dwordx2 v[38:39], v4, s[12:13] offset:1536
.Ln1_a:
	s_add_u32 s22, s4, s46
	s_cmp_lt_u32 s22, 0x4000
	s_cbranch_scc0 .Ln1_a_nonext
	s_lshl_b32 s5, s22, 11
	v_add_u32_e32 v5, s5, v2
	global_load_dwordx2 v[40:41], v5, s[12:13]
	global_load_dwordx2 v[42:43], v5, s[12:13] offset:512
	global_load_dwordx2 v[44:45], v5, s[12:13] offset:1024
	global_load_dwordx2 v[46:47], v5, s[12:13] offset:1536
	s_cmp_eq_u32 s23, 0
	s_cbranch_scc1 .Ln1_a_w4
	s_waitcnt vmcnt(8)
	s_branch .Ln1_a_have

; DI unsigned pk_bf16(float a, float b) { f32x2 v = {a, b}; bf2_t r = __builtin_convertvector(v, bf2_t); return __builtin_bit_cast(unsigned, r); }
; DI float bflo(unsigned u) { return __uint_as_float(u << 16); }
; DI float bfhi(unsigned u) { return __uint_as_float(u & 0xffff0000u); }
; DI void phase_norm1(const Params& p) {
;     ...
;     for (int tok = gw; tok < T_TOK; tok += nw) {
;         f32x4 v[4]; float ss = 0.f;
; #pragma unroll
;         for (int i = 0; i < 4; ++i) { const int c = 4 * lane + 256 * i;
;             if (tok < T_PR) { const u32x2 t = *(const u32x2*)(x1 + (size_t)tok * 1024 + c); v[i] = (f32x4){bflo(t.x), bfhi(t.x), bflo(t.y), bfhi(t.y)}; }
;             else { const size_t o = (size_t)(tok - T_PR) * 1024 + c; v[i] = *(const f32x4*)(p.xs + o);
; #pragma unroll
;                 for (int s = 0; s < 4; ++s) v[i] += *(const f32x4*)(part + (size_t)s * 1048576 + o);
;                 u32x2 t; t.x = pk_bf16(v[i].x, v[i].y); t.y = pk_bf16(v[i].z, v[i].w); *(u32x2*)(x1 + (size_t)tok * 1024 + c) = t; }
;             ss += v[i].x * v[i].x + v[i].y * v[i].y + v[i].z * v[i].z + v[i].w * v[i].w; }
;         ss = wave_sum(ss);
;         const float rstd = rsqrtf(ss * (1.f / 1024.f) + 1e-6f);
; #pragma unroll
;         for (int i = 0; i < 4; ++i) { const f32x4 ww = *(const f32x4*)(w + 4 * lane + 256 * i);
;             u32x2 o; o.x = pk_bf16(v[i].x * rstd * ww.x, v[i].y * rstd * ww.y); o.y = pk_bf16(v[i].z * rstd * ww.z, v[i].w * rstd * ww.w);
;             *(u32x2*)(out + (size_t)tok * 1024 + 4 * lane + 256 * i) = o; }
.Ln1_a_have:
	s_mov_b32 s23, 1
	v_lshlrev_b32_e32 v64, 16, v32
	v_and_b32_e32 v65, 0xffff0000, v32
	v_lshlrev_b32_e32 v66, 16, v33
	v_and_b32_e32 v67, 0xffff0000, v33
	v_lshlrev_b32_e32 v68, 16, v34
	v_and_b32_e32 v69, 0xffff0000, v34
	v_lshlrev_b32_e32 v70, 16, v35
	v_and_b32_e32 v71, 0xffff0000, v35
	v_lshlrev_b32_e32 v72, 16, v36
	v_and_b32_e32 v73, 0xffff0000, v36
	v_lshlrev_b32_e32 v74, 16, v37
	v_and_b32_e32 v75, 0xffff0000, v37
	v_lshlrev_b32_e32 v76, 16, v38
	v_and_b32_e32 v77, 0xffff0000, v38
	v_lshlrev_b32_e32 v78, 16, v39
	v_and_b32_e32 v79, 0xffff0000, v39
	v_mul_f32_e32 v48, v64, v64
	v_fmac_f32_e32 v48, v65, v65
	v_fmac_f32_e32 v48, v66, v66
	v_fmac_f32_e32 v48, v67, v67
	v_mul_f32_e32 v49, v68, v68
	v_fmac_f32_e32 v49, v69, v69
	v_fmac_f32_e32 v49, v70, v70
	v_fmac_f32_e32 v49, v71, v71
	v_mul_f32_e32 v50, v72, v72
	v_fmac_f32_e32 v50, v73, v73
	v_fmac_f32_e32 v50, v74, v74
	v_fmac_f32_e32 v50, v75, v75
	v_mul_f32_e32 v51, v76, v76
	v_fmac_f32_e32 v51, v77, v77
	v_fmac_f32_e32 v51, v78, v78
	v_fmac_f32_e32 v51, v79, v79
	v_add_f32_e32 v48, v48, v49
	v_add_f32_e32 v50, v50, v51
	v_add_f32_e32 v48, v48, v50
	s_nop 1
	v_add_f32_dpp v48, v48, v48 quad_perm:[1,0,3,2] row_mask:0xf bank_mask:0xf bound_ctrl:1
	s_nop 1
	v_add_f32_dpp v48, v48, v48 quad_perm:[2,3,0,1] row_mask:0xf bank_mask:0xf bound_ctrl:1
	s_nop 1
	v_add_f32_dpp v48, v48, v48 row_ror:4 row_mask:0xf bank_mask:0xf bound_ctrl:1
	s_nop 1
	v_add_f32_dpp v48, v48, v48 row_ror:8 row_mask:0xf bank_mask:0xf bound_ctrl:1
	s_nop 1
	v_readlane_b32 s28, v48, 0
	v_readlane_b32 s29, v48, 16
	v_readlane_b32 s30, v48, 32
	v_readlane_b32 s31, v48, 48
	s_nop 1
	v_mov_b32_e32 v52, s28
	v_add_f32_e32 v52, s29, v52
	v_add_f32_e32 v52, s30, v52
	v_add_f32_e32 v52, s31, v52
	v_fmamk_f32 v52, v52, 0x3a800000, v60
	v_rsq_f32_e32 v52, v52
	s_lshl_b32 s20, s4, 11
	s_add_u32 s20, s16, s20
	s_addc_u32 s21, s17, 0
	v_mul_f32_e32 v64, v64, v52
	v_mul_f32_e32 v65, v65, v52
	v_mul_f32_e32 v66, v66, v52
	v_mul_f32_e32 v67, v67, v52
	v_mul_f32_e32 v64, v64, v16
	v_mul_f32_e32 v65, v65, v17
	v_mul_f32_e32 v66, v66, v18
	v_mul_f32_e32 v67, v67, v19
	v_cvt_pk_bf16_f32 v64, v64, v65
	v_cvt_pk_bf16_f32 v65, v66, v67
	global_store_dwordx2 v2, v[64:65], s[20:21]
	v_mul_f32_e32 v68, v68, v52
	v_mul_f32_e32 v69, v69, v52
	v_mul_f32_e32 v70, v70, v52
	v_mul_f32_e32 v71, v71, v52
	v_mul_f32_e32 v68, v68, v20
	v_mul_f32_e32 v69, v69, v21
	v_mul_f32_e32 v70, v70, v22
	v_mul_f32_e32 v71, v71, v23
	v_cvt_pk_bf16_f32 v68, v68, v69
	v_cvt_pk_bf16_f32 v69, v70, v71
	global_store_dwordx2 v2, v[68:69], s[20:21] offset:512
	v_mul_f32_e32 v72, v72, v52
	v_mul_f32_e32 v73, v73, v52
	v_mul_f32_e32 v74, v74, v52
	v_mul_f32_e32 v75, v75, v52
	v_mul_f32_e32 v72, v72, v24
	v_mul_f32_e32 v73, v73, v25
	v_mul_f32_e32 v74, v74, v26
	v_mul_f32_e32 v75, v75, v27
	v_cvt_pk_bf16_f32 v72, v72, v73
	v_cvt_pk_bf16_f32 v73, v74, v75
	global_store_dwordx2 v2, v[72:73], s[20:21] offset:1024
	v_mul_f32_e32 v76, v76, v52
	v_mul_f32_e32 v77, v77, v52
	v_mul_f32_e32 v78, v78, v52
	v_mul_f32_e32 v79, v79, v52
	v_mul_f32_e32 v76, v76, v28
	v_mul_f32_e32 v77, v77, v29
	v_mul_f32_e32 v78, v78, v30
	v_mul_f32_e32 v79, v79, v31
	v_cvt_pk_bf16_f32 v76, v76, v77
	v_cvt_pk_bf16_f32 v77, v78, v79
	global_store_dwordx2 v2, v[76:77], s[20:21] offset:1536
	s_mov_b32 s4, s22
	s_cmp_lt_u32 s4, 0x4000
	s_cbranch_scc0 .Ln1_sample
.Ln1_b:
	s_add_u32 s22, s4, s46
	s_cmp_lt_u32 s22, 0x4000
	s_cbranch_scc0 .Ln1_b_nonext
	s_lshl_b32 s5, s22, 11
	v_add_u32_e32 v5, s5, v2
	global_load_dwordx2 v[32:33], v5, s[12:13]
	global_load_dwordx2 v[34:35], v5, s[12:13] offset:512
	global_load_dwordx2 v[36:37], v5, s[12:13] offset:1024
	global_load_dwordx2 v[38:39], v5, s[12:13] offset:1536
	s_cmp_eq_u32 s23, 0
	s_cbranch_scc1 .Ln1_b_w4
	s_waitcnt vmcnt(8)
	s_branch .Ln1_b_have

; DI unsigned pk_bf16(float a, float b) { f32x2 v = {a, b}; bf2_t r = __builtin_convertvector(v, bf2_t); return __builtin_bit_cast(unsigned, r); }
; DI float bflo(unsigned u) { return __uint_as_float(u << 16); }
; DI float bfhi(unsigned u) { return __uint_as_float(u & 0xffff0000u); }
; DI void phase_norm1(const Params& p) {
;     ...
;     for (int tok = gw; tok < T_TOK; tok += nw) {
;         f32x4 v[4]; float ss = 0.f;
; #pragma unroll
;         for (int i = 0; i < 4; ++i) { const int c = 4 * lane + 256 * i;
;             if (tok < T_PR) { const u32x2 t = *(const u32x2*)(x1 + (size_t)tok * 1024 + c); v[i] = (f32x4){bflo(t.x), bfhi(t.x), bflo(t.y), bfhi(t.y)}; }
;             else { const size_t o = (size_t)(tok - T_PR) * 1024 + c; v[i] = *(const f32x4*)(p.xs + o);
; #pragma unroll
;                 for (int s = 0; s < 4; ++s) v[i] += *(const f32x4*)(part + (size_t)s * 1048576 + o);
;                 u32x2 t; t.x = pk_bf16(v[i].x, v[i].y); t.y = pk_bf16(v[i].z, v[i].w); *(u32x2*)(x1 + (size_t)tok * 1024 + c) = t; }
;             ss += v[i].x * v[i].x + v[i].y * v[i].y + v[i].z * v[i].z + v[i].w * v[i].w; }
;         ss = wave_sum(ss);
;         const float rstd = rsqrtf(ss * (1.f / 1024.f) + 1e-6f);
; #pragma unroll
;         for (int i = 0; i < 4; ++i) { const f32x4 ww = *(const f32x4*)(w + 4 * lane + 256 * i);
;             u32x2 o; o.x = pk_bf16(v[i].x * rstd * ww.x, v[i].y * rstd * ww.y); o.y = pk_bf16(v[i].z * rstd * ww.z, v[i].w * rstd * ww.w);
;             *(u32x2*)(out + (size_t)tok * 1024 + 4 * lane + 256 * i) = o; }
.Ln1_b_have:
	s_mov_b32 s23, 1
	v_lshlrev_b32_e32 v64, 16, v40
	v_and_b32_e32 v65, 0xffff0000, v40
	v_lshlrev_b32_e32 v66, 16, v41
	v_and_b32_e32 v67, 0xffff0000, v41
	v_lshlrev_b32_e32 v68, 16, v42
	v_and_b32_e32 v69, 0xffff0000, v42
	v_lshlrev_b32_e32 v70, 16, v43
	v_and_b32_e32 v71, 0xffff0000, v43
	v_lshlrev_b32_e32 v72, 16, v44
	v_and_b32_e32 v73, 0xffff0000, v44
	v_lshlrev_b32_e32 v74, 16, v45
	v_and_b32_e32 v75, 0xffff0000, v45
	v_lshlrev_b32_e32 v76, 16, v46
	v_and_b32_e32 v77, 0xffff0000, v46
	v_lshlrev_b32_e32 v78, 16, v47
	v_and_b32_e32 v79, 0xffff0000, v47
	v_mul_f32_e32 v48, v64, v64
	v_fmac_f32_e32 v48, v65, v65
	v_fmac_f32_e32 v48, v66, v66
	v_fmac_f32_e32 v48, v67, v67
	v_mul_f32_e32 v49, v68, v68
	v_fmac_f32_e32 v49, v69, v69
	v_fmac_f32_e32 v49, v70, v70
	v_fmac_f32_e32 v49, v71, v71
	v_mul_f32_e32 v50, v72, v72
	v_fmac_f32_e32 v50, v73, v73
	v_fmac_f32_e32 v50, v74, v74
	v_fmac_f32_e32 v50, v75, v75
	v_mul_f32_e32 v51, v76, v76
	v_fmac_f32_e32 v51, v77, v77
	v_fmac_f32_e32 v51, v78, v78
	v_fmac_f32_e32 v51, v79, v79
	v_add_f32_e32 v48, v48, v49
	v_add_f32_e32 v50, v50, v51
	v_add_f32_e32 v48, v48, v50
	s_nop 1
	v_add_f32_dpp v48, v48, v48 quad_perm:[1,0,3,2] row_mask:0xf bank_mask:0xf bound_ctrl:1
	s_nop 1
	v_add_f32_dpp v48, v48, v48 quad_perm:[2,3,0,1] row_mask:0xf bank_mask:0xf bound_ctrl:1
	s_nop 1
	v_add_f32_dpp v48, v48, v48 row_ror:4 row_mask:0xf bank_mask:0xf bound_ctrl:1
	s_nop 1
	v_add_f32_dpp v48, v48, v48 row_ror:8 row_mask:0xf bank_mask:0xf bound_ctrl:1
	s_nop 1
	v_readlane_b32 s28, v48, 0
	v_readlane_b32 s29, v48, 16
	v_readlane_b32 s30, v48, 32
	v_readlane_b32 s31, v48, 48
	s_nop 1
	v_mov_b32_e32 v52, s28
	v_add_f32_e32 v52, s29, v52
	v_add_f32_e32 v52, s30, v52
	v_add_f32_e32 v52, s31, v52
	v_fmamk_f32 v52, v52, 0x3a800000, v60
	v_rsq_f32_e32 v52, v52
	s_lshl_b32 s20, s4, 11
	s_add_u32 s20, s16, s20
	s_addc_u32 s21, s17, 0
	v_mul_f32_e32 v64, v64, v52
	v_mul_f32_e32 v65, v65, v52
	v_mul_f32_e32 v66, v66, v52
	v_mul_f32_e32 v67, v67, v52
	v_mul_f32_e32 v64, v64, v16
	v_mul_f32_e32 v65, v65, v17
	v_mul_f32_e32 v66, v66, v18
	v_mul_f32_e32 v67, v67, v19
	v_cvt_pk_bf16_f32 v64, v64, v65
	v_cvt_pk_bf16_f32 v65, v66, v67
	global_store_dwordx2 v2, v[64:65], s[20:21]
	v_mul_f32_e32 v68, v68, v52
	v_mul_f32_e32 v69, v69, v52
	v_mul_f32_e32 v70, v70, v52
	v_mul_f32_e32 v71, v71, v52
	v_mul_f32_e32 v68, v68, v20
	v_mul_f32_e32 v69, v69, v21
	v_mul_f32_e32 v70, v70, v22
	v_mul_f32_e32 v71, v71, v23
	v_cvt_pk_bf16_f32 v68, v68, v69
	v_cvt_pk_bf16_f32 v69, v70, v71
	global_store_dwordx2 v2, v[68:69], s[20:21] offset:512
	v_mul_f32_e32 v72, v72, v52
	v_mul_f32_e32 v73, v73, v52
	v_mul_f32_e32 v74, v74, v52
	v_mul_f32_e32 v75, v75, v52
	v_mul_f32_e32 v72, v72, v24
	v_mul_f32_e32 v73, v73, v25
	v_mul_f32_e32 v74, v74, v26
	v_mul_f32_e32 v75, v75, v27
	v_cvt_pk_bf16_f32 v72, v72, v73
	v_cvt_pk_bf16_f32 v73, v74, v75
	global_store_dwordx2 v2, v[72:73], s[20:21] offset:1024
	v_mul_f32_e32 v76, v76, v52
	v_mul_f32_e32 v77, v77, v52
	v_mul_f32_e32 v78, v78, v52
	v_mul_f32_e32 v79, v79, v52
	v_mul_f32_e32 v76, v76, v28
	v_mul_f32_e32 v77, v77, v29
	v_mul_f32_e32 v78, v78, v30
	v_mul_f32_e32 v79, v79, v31
	v_cvt_pk_bf16_f32 v76, v76, v77
	v_cvt_pk_bf16_f32 v77, v78, v79
	global_store_dwordx2 v2, v[76:77], s[20:21] offset:1536
	s_mov_b32 s4, s22
	s_cmp_lt_u32 s4, 0x4000
	s_cbranch_scc1 .Ln1_a
.Ln1_sample:
	s_cmp_lt_u32 s4, 0x4400
	s_cbranch_scc0 .Ln1_done
	s_sub_u32 s5, s4, 0x4000
	s_lshl_b32 s5, s5, 12
	s_add_u32 s24, s62, s5
	s_addc_u32 s25, s63, 0
	global_load_dwordx4 v[64:67], v3, s[24:25]
	global_load_dwordx4 v[68:71], v3, s[24:25] offset:1024
	global_load_dwordx4 v[72:75], v3, s[24:25] offset:2048
	global_load_dwordx4 v[76:79], v3, s[24:25] offset:3072
	s_add_u32 s24, s78, 0x26500000
	s_addc_u32 s25, s79, 0
	s_add_u32 s24, s24, s5
	s_addc_u32 s25, s25, 0
	global_load_dwordx4 v[80:83], v3, s[24:25]
	global_load_dwordx4 v[84:87], v3, s[24:25] offset:1024
	global_load_dwordx4 v[88:91], v3, s[24:25] offset:2048
	global_load_dwordx4 v[92:95], v3, s[24:25] offset:3072
	s_add_u32 s24, s24, 0x400000
	s_addc_u32 s25, s25, 0
	global_load_dwordx4 v[96:99], v3, s[24:25]
	global_load_dwordx4 v[100:103], v3, s[24:25] offset:1024
	global_load_dwordx4 v[104:107], v3, s[24:25] offset:2048
	global_load_dwordx4 v[108:111], v3, s[24:25] offset:3072
	s_add_u32 s24, s24, 0x400000
	s_addc_u32 s25, s25, 0
	global_load_dwordx4 v[112:115], v3, s[24:25]
	global_load_dwordx4 v[116:119], v3, s[24:25] offset:1024
	global_load_dwordx4 v[120:123], v3, s[24:25] offset:2048
	global_load_dwordx4 v[124:127], v3, s[24:25] offset:3072
	s_add_u32 s24, s24, 0x400000
	s_addc_u32 s25, s25, 0
	global_load_dwordx4 v[128:131], v3, s[24:25]
	global_load_dwordx4 v[132:135], v3, s[24:25] offset:1024
	global_load_dwordx4 v[136:139], v3, s[24:25] offset:2048
	global_load_dwordx4 v[140:143], v3, s[24:25] offset:3072
	s_waitcnt vmcnt(0)
; DI unsigned pk_bf16(float a, float b) { f32x2 v = {a, b}; bf2_t r = __builtin_convertvector(v, bf2_t); return __builtin_bit_cast(unsigned, r); }
; DI void phase_norm1(const Params& p) {
;     ...
;             else { const size_t o = (size_t)(tok - T_PR) * 1024 + c; v[i] = *(const f32x4*)(p.xs + o);
; #pragma unroll
;                 for (int s = 0; s < 4; ++s) v[i] += *(const f32x4*)(part + (size_t)s * 1048576 + o);
;                 u32x2 t; t.x = pk_bf16(v[i].x, v[i].y); t.y = pk_bf16(v[i].z, v[i].w); *(u32x2*)(x1 + (size_t)tok * 1024 + c) = t; }
;             ss += v[i].x * v[i].x + v[i].y * v[i].y + v[i].z * v[i].z + v[i].w * v[i].w; }
;         ss = wave_sum(ss);
;         const float rstd = rsqrtf(ss * (1.f / 1024.f) + 1e-6f);
; #pragma unroll
;         for (int i = 0; i < 4; ++i) { const f32x4 ww = *(const f32x4*)(w + 4 * lane + 256 * i);
;             u32x2 o; o.x = pk_bf16(v[i].x * rstd * ww.x, v[i].y * rstd * ww.y); o.y = pk_bf16(v[i].z * rstd * ww.z, v[i].w * rstd * ww.w);
;             *(u32x2*)(out + (size_t)tok * 1024 + 4 * lane + 256 * i) = o; }
	v_add_f32_e32 v64, v64, v80
	v_add_f32_e32 v65, v65, v81
	v_add_f32_e32 v66, v66, v82
	v_add_f32_e32 v67, v67, v83
	v_add_f32_e32 v68, v68, v84
	v_add_f32_e32 v69, v69, v85
	v_add_f32_e32 v70, v70, v86
	v_add_f32_e32 v71, v71, v87
	v_add_f32_e32 v72, v72, v88
	v_add_f32_e32 v73, v73, v89
	v_add_f32_e32 v74, v74, v90
	v_add_f32_e32 v75, v75, v91
	v_add_f32_e32 v76, v76, v92
	v_add_f32_e32 v77, v77, v93
	v_add_f32_e32 v78, v78, v94
	v_add_f32_e32 v79, v79, v95
	v_add_f32_e32 v64, v64, v96
	v_add_f32_e32 v65, v65, v97
	v_add_f32_e32 v66, v66, v98
	v_add_f32_e32 v67, v67, v99
	v_add_f32_e32 v68, v68, v100
	v_add_f32_e32 v69, v69, v101
	v_add_f32_e32 v70, v70, v102
	v_add_f32_e32 v71, v71, v103
	v_add_f32_e32 v72, v72, v104
	v_add_f32_e32 v73, v73, v105
	v_add_f32_e32 v74, v74, v106
	v_add_f32_e32 v75, v75, v107
	v_add_f32_e32 v76, v76, v108
	v_add_f32_e32 v77, v77, v109
	v_add_f32_e32 v78, v78, v110
	v_add_f32_e32 v79, v79, v111
	v_add_f32_e32 v64, v64, v112
	v_add_f32_e32 v65, v65, v113
	v_add_f32_e32 v66, v66, v114
	v_add_f32_e32 v67, v67, v115
	v_add_f32_e32 v68, v68, v116
	v_add_f32_e32 v69, v69, v117
	v_add_f32_e32 v70, v70, v118
	v_add_f32_e32 v71, v71, v119
	v_add_f32_e32 v72, v72, v120
	v_add_f32_e32 v73, v73, v121
	v_add_f32_e32 v74, v74, v122
	v_add_f32_e32 v75, v75, v123
	v_add_f32_e32 v76, v76, v124
	v_add_f32_e32 v77, v77, v125
	v_add_f32_e32 v78, v78, v126
	v_add_f32_e32 v79, v79, v127
	v_add_f32_e32 v64, v64, v128
	v_add_f32_e32 v65, v65, v129
	v_add_f32_e32 v66, v66, v130
	v_add_f32_e32 v67, v67, v131
	v_add_f32_e32 v68, v68, v132
	v_add_f32_e32 v69, v69, v133
	v_add_f32_e32 v70, v70, v134
	v_add_f32_e32 v71, v71, v135
	v_add_f32_e32 v72, v72, v136
	v_add_f32_e32 v73, v73, v137
	v_add_f32_e32 v74, v74, v138
	v_add_f32_e32 v75, v75, v139
	v_add_f32_e32 v76, v76, v140
	v_add_f32_e32 v77, v77, v141
	v_add_f32_e32 v78, v78, v142
	v_add_f32_e32 v79, v79, v143
	s_lshl_b32 s26, s4, 11
	s_add_u32 s26, s12, s26
	s_addc_u32 s27, s13, 0
	v_cvt_pk_bf16_f32 v144, v64, v65
	v_cvt_pk_bf16_f32 v145, v66, v67
	global_store_dwordx2 v2, v[144:145], s[26:27]
	v_cvt_pk_bf16_f32 v146, v68, v69
	v_cvt_pk_bf16_f32 v147, v70, v71
	global_store_dwordx2 v2, v[146:147], s[26:27] offset:512
	v_cvt_pk_bf16_f32 v148, v72, v73
	v_cvt_pk_bf16_f32 v149, v74, v75
	global_store_dwordx2 v2, v[148:149], s[26:27] offset:1024
	v_cvt_pk_bf16_f32 v150, v76, v77
	v_cvt_pk_bf16_f32 v151, v78, v79
	global_store_dwordx2 v2, v[150:151], s[26:27] offset:1536
	v_mul_f32_e32 v48, v64, v64
	v_fmac_f32_e32 v48, v65, v65
	v_fmac_f32_e32 v48, v66, v66
	v_fmac_f32_e32 v48, v67, v67
	v_mul_f32_e32 v49, v68, v68
	v_fmac_f32_e32 v49, v69, v69
	v_fmac_f32_e32 v49, v70, v70
	v_fmac_f32_e32 v49, v71, v71
	v_mul_f32_e32 v50, v72, v72
	v_fmac_f32_e32 v50, v73, v73
	v_fmac_f32_e32 v50, v74, v74
	v_fmac_f32_e32 v50, v75, v75
	v_mul_f32_e32 v51, v76, v76
	v_fmac_f32_e32 v51, v77, v77
	v_fmac_f32_e32 v51, v78, v78
	v_fmac_f32_e32 v51, v79, v79
	v_add_f32_e32 v48, v48, v49
	v_add_f32_e32 v50, v50, v51
	v_add_f32_e32 v48, v48, v50
	s_nop 1
	v_add_f32_dpp v48, v48, v48 quad_perm:[1,0,3,2] row_mask:0xf bank_mask:0xf bound_ctrl:1
	s_nop 1
	v_add_f32_dpp v48, v48, v48 quad_perm:[2,3,0,1] row_mask:0xf bank_mask:0xf bound_ctrl:1
	s_nop 1
	v_add_f32_dpp v48, v48, v48 row_ror:4 row_mask:0xf bank_mask:0xf bound_ctrl:1
	s_nop 1
	v_add_f32_dpp v48, v48, v48 row_ror:8 row_mask:0xf bank_mask:0xf bound_ctrl:1
	s_nop 1
	v_readlane_b32 s28, v48, 0
	v_readlane_b32 s29, v48, 16
	v_readlane_b32 s30, v48, 32
	v_readlane_b32 s31, v48, 48
	s_nop 1
	v_mov_b32_e32 v52, s28
	v_add_f32_e32 v52, s29, v52
	v_add_f32_e32 v52, s30, v52
	v_add_f32_e32 v52, s31, v52
	v_fmamk_f32 v52, v52, 0x3a800000, v60
	v_rsq_f32_e32 v52, v52
	s_lshl_b32 s20, s4, 11
	s_add_u32 s20, s16, s20
	s_addc_u32 s21, s17, 0
	v_mul_f32_e32 v64, v64, v52
	v_mul_f32_e32 v65, v65, v52
	v_mul_f32_e32 v66, v66, v52
	v_mul_f32_e32 v67, v67, v52
	v_mul_f32_e32 v64, v64, v16
	v_mul_f32_e32 v65, v65, v17
	v_mul_f32_e32 v66, v66, v18
	v_mul_f32_e32 v67, v67, v19
	v_cvt_pk_bf16_f32 v64, v64, v65
	v_cvt_pk_bf16_f32 v65, v66, v67
	global_store_dwordx2 v2, v[64:65], s[20:21]
	v_mul_f32_e32 v68, v68, v52
	v_mul_f32_e32 v69, v69, v52
	v_mul_f32_e32 v70, v70, v52
	v_mul_f32_e32 v71, v71, v52
	v_mul_f32_e32 v68, v68, v20
	v_mul_f32_e32 v69, v69, v21
	v_mul_f32_e32 v70, v70, v22
	v_mul_f32_e32 v71, v71, v23
	v_cvt_pk_bf16_f32 v68, v68, v69
	v_cvt_pk_bf16_f32 v69, v70, v71
	global_store_dwordx2 v2, v[68:69], s[20:21] offset:512
	v_mul_f32_e32 v72, v72, v52
	v_mul_f32_e32 v73, v73, v52
	v_mul_f32_e32 v74, v74, v52
	v_mul_f32_e32 v75, v75, v52
	v_mul_f32_e32 v72, v72, v24
	v_mul_f32_e32 v73, v73, v25
	v_mul_f32_e32 v74, v74, v26
	v_mul_f32_e32 v75, v75, v27
	v_cvt_pk_bf16_f32 v72, v72, v73
	v_cvt_pk_bf16_f32 v73, v74, v75
	global_store_dwordx2 v2, v[72:73], s[20:21] offset:1024
	v_mul_f32_e32 v76, v76, v52
	v_mul_f32_e32 v77, v77, v52
	v_mul_f32_e32 v78, v78, v52
	v_mul_f32_e32 v79, v79, v52
	v_mul_f32_e32 v76, v76, v28
	v_mul_f32_e32 v77, v77, v29
	v_mul_f32_e32 v78, v78, v30
	v_mul_f32_e32 v79, v79, v31
	v_cvt_pk_bf16_f32 v76, v76, v77
	v_cvt_pk_bf16_f32 v77, v78, v79
	global_store_dwordx2 v2, v[76:77], s[20:21] offset:1536
.Ln1_done:
.LBB0_1114:
	s_or_b64 exec, exec, s[8:9]
	s_cmp_gt_i32 s81, 7
	s_cselect_b64 s[4:5], -1, 0
	s_and_b64 s[0:1], s[6:7], s[4:5]
	s_andn2_b64 vcc, exec, s[0:1]
	s_cbranch_vccnz .LBB0_1182
	s_cmp_eq_u32 s82, 0
	s_cbranch_scc1 .LBB0_1127
	v_lshrrev_b32_e32 v2, 20, v0
	v_lshrrev_b32_e32 v3, 10, v0
	v_or_b32_e32 v2, v3, v2
	s_movk_i32 s0, 0x3ff
	v_and_or_b32 v2, v2, s0, v1
	v_cmp_eq_u32_e32 vcc, 0, v2
	s_waitcnt vmcnt(0) lgkmcnt(0)
	s_barrier
	s_and_saveexec_b64 s[0:1], vcc
	s_cbranch_execz .LBB0_1126
	v_readlane_b32 s6, v238, 0
	v_readlane_b32 s7, v238, 1
	buffer_wbl2 sc1
	s_load_dwordx2 s[6:7], s[6:7], 0x58
	v_mov_b32_e32 v4, 0
	s_mov_b64 s[8:9], exec
	v_mbcnt_lo_u32_b32 v3, s8, 0
	v_mbcnt_hi_u32_b32 v3, s9, v3
	s_waitcnt lgkmcnt(0)
	global_load_dword v2, v4, s[6:7] offset:40
	v_cmp_eq_u32_e32 vcc, 0, v3
	s_and_saveexec_b64 s[10:11], vcc
	s_cbranch_execz .LBB0_1119
	s_bcnt1_i32_b64 s3, s[8:9]
	v_mov_b32_e32 v5, s3
	global_atomic_add v5, v4, v5, s[6:7] offset:32 sc0

; #define PG8_STAGE(bufoff, gbase, voff) do { _Pragma("unroll") for (int _i = 0; _i < 2; ++_i) \
;         __builtin_amdgcn_global_load_lds((const unsigned*)((const char*)(gbase) + (voff)[_i]), (LAS unsigned*)(lds + (bufoff) + ldsw + _i * 8192), 16, 0, 0); } while (0)
; #define PG8_LDA(dst, b, h) do { _Pragma("unroll") for (int m = 0; m < 4; ++m) _Pragma("unroll") for (int k = 0; k < 2; ++k) dst[m][k] = *(const LAS bf16x8*)(lds + PG8_SA(b, h) + aoff + m * 2048 + k * 1024); } while (0)
; #define PG8_LDB(dst, b, h) do { _Pragma("unroll") for (int n = 0; n < 2; ++n) _Pragma("unroll") for (int k = 0; k < 2; ++k) dst[n][k] = *(const LAS bf16x8*)(lds + PG8_SB(b, h) + boff + n * 2048 + k * 1024); } while (0)
; #define PG8_MMA(ai, bj, At, Bt) do { __builtin_amdgcn_s_setprio(1); _Pragma("unroll") for (int m = 0; m < 4; ++m) _Pragma("unroll") for (int n = 0; n < 2; ++n) _Pragma("unroll") for (int k = 0; k < 2; ++k) \
;         acc[ai][bj][m][n] = __builtin_amdgcn_mfma_f32_16x16x32_bf16(Bt[n][k], At[m][k], acc[ai][bj][m][n], 0, 0, 0); __builtin_amdgcn_s_setprio(0); } while (0)
; #define PG8_WAIT_V(n) asm volatile("s_waitcnt vmcnt(" #n ")" ::: "memory")
; #define PG8_WAIT_L(n) asm volatile("s_waitcnt lgkmcnt(" #n ")" ::: "memory")
; #define PG8_BAR __builtin_amdgcn_s_barrier()
; #define PG8_SCHED __builtin_amdgcn_sched_barrier(0)
; template <class Epi, class Sched>
; DI void gemm_phase(LAS unsigned char* lds, const Gemm g, const Sched& S, const Epi& E) {
;     ...
;             PG8_LDB(B0, 0, 0); PG8_SCHED; PG8_LDA(At, 0, 0); PG8_STAGE(PG8_SA(1, 1), a1 + hstep, voffA);
;             PG8_WAIT_L(8); PG8_BAR; PG8_WAIT_L(0); PG8_MMA(0, 0, At, B0); PG8_BAR; PG8_SCHED;
;             PG8_LDB(B1, 0, 1); PG8_STAGE(PG8_SB(0, 0), b2, voffB);
;             PG8_BAR; PG8_WAIT_L(0); PG8_MMA(0, 1, At, B1); PG8_BAR;
;             PG8_LDA(At, 0, 1); PG8_STAGE(PG8_SA(0, 0), a2, voffA);
;             PG8_BAR; PG8_WAIT_L(0); PG8_MMA(1, 0, At, B0); PG8_BAR; PG8_SCHED;
;             PG8_STAGE(PG8_SB(0, 1), b2 + hstep, voffB);
;             PG8_WAIT_V(6); PG8_BAR; PG8_MMA(1, 1, At, B1); PG8_BAR;
.LBB0_1523:
	ds_read_b128 v[140:143], v146
	ds_read_b128 v[150:153], v146 offset:1024
	ds_read_b128 v[154:157], v146 offset:2048
	ds_read_b128 v[158:161], v146 offset:3072
	s_add_u32 s50, s42, 0xfff80080
	s_addc_u32 s51, s43, -1
	s_cmp_eq_u32 s73, 28
	s_cselect_b32 s53, s67, s51
	s_cselect_b32 s52, s68, s50
	s_cselect_b32 s51, s69, s72
	s_cselect_b32 s50, s70, s71
	v_lshl_add_u64 v[202:203], s[42:43], 0, v[136:137]
	s_add_i32 m0, s47, 0xc000
	ds_read_b128 v[168:171], v147
	ds_read_b128 v[172:175], v147 offset:1024
	ds_read_b128 v[176:179], v147 offset:2048
	ds_read_b128 v[180:183], v147 offset:3072
	ds_read_b128 v[184:187], v147 offset:4096
	ds_read_b128 v[188:191], v147 offset:5120
	ds_read_b128 v[192:195], v147 offset:6144
	ds_read_b128 v[198:201], v147 offset:7168
	global_load_lds_dwordx4 v[202:203], off
	v_lshl_add_u64 v[202:203], s[42:43], 0, v[138:139]
	s_add_i32 m0, s47, 0xe000
	s_nop 0
	global_load_lds_dwordx4 v[202:203], off
	s_waitcnt lgkmcnt(8)
	s_barrier
	s_waitcnt lgkmcnt(0)
	s_setprio 1
	s_waitcnt lgkmcnt(0)
	v_mfma_f32_16x16x32_bf16 v[126:129], v[140:143], v[168:171], v[126:129]
	v_mfma_f32_16x16x32_bf16 v[122:125], v[154:157], v[168:171], v[122:125]
	v_mfma_f32_16x16x32_bf16 v[110:113], v[140:143], v[176:179], v[110:113]
	v_mfma_f32_16x16x32_bf16 v[106:109], v[154:157], v[176:179], v[106:109]
	v_mfma_f32_16x16x32_bf16 v[94:97], v[140:143], v[184:187], v[94:97]
	v_mfma_f32_16x16x32_bf16 v[90:93], v[154:157], v[184:187], v[90:93]
	v_mfma_f32_16x16x32_bf16 v[78:81], v[140:143], v[192:195], v[78:81]
	v_mfma_f32_16x16x32_bf16 v[74:77], v[154:157], v[192:195], v[74:77]
	v_mfma_f32_16x16x32_bf16 v[126:129], v[150:153], v[172:175], v[126:129]
	v_mfma_f32_16x16x32_bf16 v[122:125], v[158:161], v[172:175], v[122:125]
	v_mfma_f32_16x16x32_bf16 v[110:113], v[150:153], v[180:183], v[110:113]
	v_mfma_f32_16x16x32_bf16 v[106:109], v[158:161], v[180:183], v[106:109]
	v_mfma_f32_16x16x32_bf16 v[94:97], v[150:153], v[188:191], v[94:97]
	v_mfma_f32_16x16x32_bf16 v[90:93], v[158:161], v[188:191], v[90:93]
	v_mfma_f32_16x16x32_bf16 v[78:81], v[150:153], v[198:201], v[78:81]
	v_mfma_f32_16x16x32_bf16 v[74:77], v[158:161], v[198:201], v[74:77]
	s_setprio 0
	s_barrier
	s_add_i32 s83, s63, s33
	v_lshl_add_u64 v[218:219], s[50:51], 0, v[132:133]
	s_mov_b32 m0, s83
	ds_read_b128 v[202:205], v148
	ds_read_b128 v[206:209], v148 offset:1024
	ds_read_b128 v[210:213], v148 offset:2048
	ds_read_b128 v[214:217], v148 offset:3072
	global_load_lds_dwordx4 v[218:219], off
	v_lshl_add_u64 v[220:221], s[50:51], 0, v[130:131]
	s_add_i32 m0, s83, 0x2000
	s_nop 0
	global_load_lds_dwordx4 v[220:221], off
	s_barrier
	s_waitcnt lgkmcnt(0)
	s_setprio 1
	s_waitcnt lgkmcnt(0)
	v_mfma_f32_16x16x32_bf16 v[118:121], v[202:205], v[168:171], v[118:121]
	v_mfma_f32_16x16x32_bf16 v[114:117], v[210:213], v[168:171], v[114:117]
	v_mfma_f32_16x16x32_bf16 v[102:105], v[202:205], v[176:179], v[102:105]
	v_mfma_f32_16x16x32_bf16 v[98:101], v[210:213], v[176:179], v[98:101]
	v_mfma_f32_16x16x32_bf16 v[86:89], v[202:205], v[184:187], v[86:89]
	v_mfma_f32_16x16x32_bf16 v[82:85], v[210:213], v[184:187], v[82:85]
	v_mfma_f32_16x16x32_bf16 v[70:73], v[202:205], v[192:195], v[70:73]
	v_mfma_f32_16x16x32_bf16 v[66:69], v[210:213], v[192:195], v[66:69]
	v_mfma_f32_16x16x32_bf16 v[118:121], v[206:209], v[172:175], v[118:121]
	v_mfma_f32_16x16x32_bf16 v[114:117], v[214:217], v[172:175], v[114:117]
	v_mfma_f32_16x16x32_bf16 v[102:105], v[206:209], v[180:183], v[102:105]
	v_mfma_f32_16x16x32_bf16 v[98:101], v[214:217], v[180:183], v[98:101]
	v_mfma_f32_16x16x32_bf16 v[86:89], v[206:209], v[188:191], v[86:89]
	v_mfma_f32_16x16x32_bf16 v[82:85], v[214:217], v[188:191], v[82:85]
	v_mfma_f32_16x16x32_bf16 v[70:73], v[206:209], v[198:201], v[70:73]
	v_mfma_f32_16x16x32_bf16 v[66:69], v[214:217], v[198:201], v[66:69]
	s_setprio 0
	s_mov_b32 m0, s47
	v_lshl_add_u64 v[222:223], s[52:53], 0, v[132:133]
	s_barrier
	ds_read_b128 v[168:171], v147 offset:16384
	ds_read_b128 v[172:175], v147 offset:17408
	ds_read_b128 v[176:179], v147 offset:18432
	ds_read_b128 v[180:183], v147 offset:19456
	ds_read_b128 v[184:187], v147 offset:20480
	ds_read_b128 v[188:191], v147 offset:21504
	ds_read_b128 v[192:195], v147 offset:22528
	ds_read_b128 v[198:201], v147 offset:23552
	global_load_lds_dwordx4 v[222:223], off
	v_lshl_add_u64 v[224:225], s[52:53], 0, v[130:131]
	s_mov_b32 m0, s54
	s_nop 0
	global_load_lds_dwordx4 v[224:225], off
	s_barrier
	s_waitcnt lgkmcnt(0)
	s_setprio 1
	s_waitcnt lgkmcnt(0)
	v_mfma_f32_16x16x32_bf16 v[62:65], v[140:143], v[168:171], v[62:65]
	v_mfma_f32_16x16x32_bf16 v[58:61], v[154:157], v[168:171], v[58:61]
	v_mfma_f32_16x16x32_bf16 v[46:49], v[140:143], v[176:179], v[46:49]
	v_mfma_f32_16x16x32_bf16 v[42:45], v[154:157], v[176:179], v[42:45]
	v_mfma_f32_16x16x32_bf16 v[30:33], v[140:143], v[184:187], v[30:33]
	v_mfma_f32_16x16x32_bf16 v[26:29], v[154:157], v[184:187], v[26:29]
	v_mfma_f32_16x16x32_bf16 v[14:17], v[140:143], v[192:195], v[14:17]
	v_mfma_f32_16x16x32_bf16 v[10:13], v[154:157], v[192:195], v[10:13]
	v_mfma_f32_16x16x32_bf16 v[62:65], v[150:153], v[172:175], v[62:65]
	v_mfma_f32_16x16x32_bf16 v[58:61], v[158:161], v[172:175], v[58:61]
	v_mfma_f32_16x16x32_bf16 v[46:49], v[150:153], v[180:183], v[46:49]
	v_mfma_f32_16x16x32_bf16 v[42:45], v[158:161], v[180:183], v[42:45]
	v_mfma_f32_16x16x32_bf16 v[30:33], v[150:153], v[188:191], v[30:33]
	v_mfma_f32_16x16x32_bf16 v[26:29], v[158:161], v[188:191], v[26:29]
	v_mfma_f32_16x16x32_bf16 v[14:17], v[150:153], v[198:201], v[14:17]
	v_mfma_f32_16x16x32_bf16 v[10:13], v[158:161], v[198:201], v[10:13]
	s_setprio 0
	s_barrier
; #define PG8_STAGE(bufoff, gbase, voff) do { _Pragma("unroll") for (int _i = 0; _i < 2; ++_i) \
;         __builtin_amdgcn_global_load_lds((const unsigned*)((const char*)(gbase) + (voff)[_i]), (LAS unsigned*)(lds + (bufoff) + ldsw + _i * 8192), 16, 0, 0); } while (0)
; #define PG8_LDA(dst, b, h) do { _Pragma("unroll") for (int m = 0; m < 4; ++m) _Pragma("unroll") for (int k = 0; k < 2; ++k) dst[m][k] = *(const LAS bf16x8*)(lds + PG8_SA(b, h) + aoff + m * 2048 + k * 1024); } while (0)
; #define PG8_LDB(dst, b, h) do { _Pragma("unroll") for (int n = 0; n < 2; ++n) _Pragma("unroll") for (int k = 0; k < 2; ++k) dst[n][k] = *(const LAS bf16x8*)(lds + PG8_SB(b, h) + boff + n * 2048 + k * 1024); } while (0)
; #define PG8_MMA(ai, bj, At, Bt) do { __builtin_amdgcn_s_setprio(1); _Pragma("unroll") for (int m = 0; m < 4; ++m) _Pragma("unroll") for (int n = 0; n < 2; ++n) _Pragma("unroll") for (int k = 0; k < 2; ++k) \
;         acc[ai][bj][m][n] = __builtin_amdgcn_mfma_f32_16x16x32_bf16(Bt[n][k], At[m][k], acc[ai][bj][m][n], 0, 0, 0); __builtin_amdgcn_s_setprio(0); } while (0)
; #define PG8_WAIT_V(n) asm volatile("s_waitcnt vmcnt(" #n ")" ::: "memory")
; #define PG8_WAIT_L(n) asm volatile("s_waitcnt lgkmcnt(" #n ")" ::: "memory")
; #define PG8_BAR __builtin_amdgcn_s_barrier()
; #define PG8_SCHED __builtin_amdgcn_sched_barrier(0)
; template <class Epi, class Sched>
; DI void gemm_phase(LAS unsigned char* lds, const Gemm g, const Sched& S, const Epi& E) {
;     ...
;             PG8_STAGE(PG8_SB(0, 1), b2 + hstep, voffB);
;             PG8_WAIT_V(6); PG8_BAR; PG8_MMA(1, 1, At, B1); PG8_BAR;
;             PG8_LDB(B0, 1, 0); PG8_SCHED; PG8_LDA(At, 1, 0); PG8_STAGE(PG8_SA(0, 1), a2 + hstep, voffA);
;             PG8_WAIT_L(8); PG8_BAR; PG8_WAIT_L(0); PG8_MMA(0, 0, At, B0); PG8_BAR; PG8_SCHED;
;             PG8_LDB(B1, 1, 1); PG8_STAGE(PG8_SB(1, 0), b3, voffB);
;             PG8_BAR; PG8_WAIT_L(0); PG8_MMA(0, 1, At, B1); PG8_BAR;
;             PG8_LDA(At, 1, 1); PG8_STAGE(PG8_SA(1, 0), a3, voffA);
;             PG8_BAR; PG8_WAIT_L(0); PG8_MMA(1, 0, At, B0); PG8_BAR; PG8_SCHED;
	s_add_u32 s88, s50, 0x80000
	s_addc_u32 s89, s51, 0
	s_add_i32 s83, s64, s33
	v_lshl_add_u64 v[140:141], s[88:89], 0, v[132:133]
	s_mov_b32 m0, s83
	s_nop 0
	global_load_lds_dwordx4 v[140:141], off
	v_lshl_add_u64 v[140:141], s[88:89], 0, v[130:131]
	s_add_i32 m0, s83, 0x2000
	s_nop 0
	global_load_lds_dwordx4 v[140:141], off
	s_waitcnt vmcnt(6)
	s_barrier
	s_setprio 1
	v_mfma_f32_16x16x32_bf16 v[54:57], v[202:205], v[168:171], v[54:57]
	v_mfma_f32_16x16x32_bf16 v[50:53], v[210:213], v[168:171], v[50:53]
	v_mfma_f32_16x16x32_bf16 v[38:41], v[202:205], v[176:179], v[38:41]
	v_mfma_f32_16x16x32_bf16 v[34:37], v[210:213], v[176:179], v[34:37]
	v_mfma_f32_16x16x32_bf16 v[22:25], v[202:205], v[184:187], v[22:25]
	v_mfma_f32_16x16x32_bf16 v[18:21], v[210:213], v[184:187], v[18:21]
	v_mfma_f32_16x16x32_bf16 v[6:9], v[202:205], v[192:195], v[6:9]
	v_mfma_f32_16x16x32_bf16 v[2:5], v[210:213], v[192:195], v[2:5]
	v_mfma_f32_16x16x32_bf16 v[54:57], v[206:209], v[172:175], v[54:57]
	v_mfma_f32_16x16x32_bf16 v[50:53], v[214:217], v[172:175], v[50:53]
	v_mfma_f32_16x16x32_bf16 v[38:41], v[206:209], v[180:183], v[38:41]
	v_mfma_f32_16x16x32_bf16 v[34:37], v[214:217], v[180:183], v[34:37]
	v_mfma_f32_16x16x32_bf16 v[22:25], v[206:209], v[188:191], v[22:25]
	v_mfma_f32_16x16x32_bf16 v[18:21], v[214:217], v[188:191], v[18:21]
	v_mfma_f32_16x16x32_bf16 v[6:9], v[206:209], v[198:201], v[6:9]
	v_mfma_f32_16x16x32_bf16 v[2:5], v[214:217], v[198:201], v[2:5]
	s_setprio 0
	s_add_i32 s83, 0, 0x18000
	v_add_u32_e32 v134, s83, v145
	s_barrier
	ds_read_b128 v[140:143], v134
	ds_read_b128 v[150:153], v134 offset:1024
	ds_read_b128 v[154:157], v134 offset:2048
	ds_read_b128 v[158:161], v134 offset:3072
	s_add_u32 s52, s52, 0x80000
	s_addc_u32 s53, s53, 0
	s_mov_b32 m0, s55
	v_lshl_add_u64 v[202:203], s[52:53], 0, v[132:133]
	ds_read_b128 v[168:171], v147 offset:32768
	ds_read_b128 v[172:175], v147 offset:33792
	ds_read_b128 v[176:179], v147 offset:34816
	ds_read_b128 v[180:183], v147 offset:35840
	ds_read_b128 v[184:187], v147 offset:36864
	ds_read_b128 v[188:191], v147 offset:37888
	ds_read_b128 v[192:195], v147 offset:38912
	ds_read_b128 v[198:201], v147 offset:39936
	global_load_lds_dwordx4 v[202:203], off
	v_lshl_add_u64 v[202:203], s[52:53], 0, v[130:131]
	s_mov_b32 m0, s57
	s_nop 0
	global_load_lds_dwordx4 v[202:203], off
	s_waitcnt lgkmcnt(8)
	s_barrier
	s_waitcnt lgkmcnt(0)
	s_setprio 1
	s_waitcnt lgkmcnt(0)
	v_mfma_f32_16x16x32_bf16 v[126:129], v[140:143], v[168:171], v[126:129]
	v_mfma_f32_16x16x32_bf16 v[122:125], v[154:157], v[168:171], v[122:125]
	v_mfma_f32_16x16x32_bf16 v[110:113], v[140:143], v[176:179], v[110:113]
	v_mfma_f32_16x16x32_bf16 v[106:109], v[154:157], v[176:179], v[106:109]
	v_mfma_f32_16x16x32_bf16 v[94:97], v[140:143], v[184:187], v[94:97]
	v_mfma_f32_16x16x32_bf16 v[90:93], v[154:157], v[184:187], v[90:93]
	v_mfma_f32_16x16x32_bf16 v[78:81], v[140:143], v[192:195], v[78:81]
	v_mfma_f32_16x16x32_bf16 v[74:77], v[154:157], v[192:195], v[74:77]
	v_mfma_f32_16x16x32_bf16 v[126:129], v[150:153], v[172:175], v[126:129]
	v_mfma_f32_16x16x32_bf16 v[122:125], v[158:161], v[172:175], v[122:125]
	v_mfma_f32_16x16x32_bf16 v[110:113], v[150:153], v[180:183], v[110:113]
	v_mfma_f32_16x16x32_bf16 v[106:109], v[158:161], v[180:183], v[106:109]
	v_mfma_f32_16x16x32_bf16 v[94:97], v[150:153], v[188:191], v[94:97]
	v_mfma_f32_16x16x32_bf16 v[90:93], v[158:161], v[188:191], v[90:93]
	v_mfma_f32_16x16x32_bf16 v[78:81], v[150:153], v[198:201], v[78:81]
	v_mfma_f32_16x16x32_bf16 v[74:77], v[158:161], v[198:201], v[74:77]
	s_setprio 0
	s_barrier
	s_add_i32 s52, 0, 0x1c000
	s_add_i32 s53, s83, s33
	v_add_u32_e32 v134, s52, v145
	v_lshl_add_u64 v[218:219], v[218:219], 0, s[10:11]
	s_mov_b32 m0, s53
	ds_read_b128 v[202:205], v134
	ds_read_b128 v[206:209], v134 offset:1024
	ds_read_b128 v[210:213], v134 offset:2048
	ds_read_b128 v[214:217], v134 offset:3072
	global_load_lds_dwordx4 v[218:219], off
	v_lshl_add_u64 v[218:219], v[220:221], 0, s[10:11]
	s_add_i32 m0, s53, 0x2000
	s_nop 0
	global_load_lds_dwordx4 v[218:219], off
	s_barrier
	s_waitcnt lgkmcnt(0)
	s_setprio 1
	s_waitcnt lgkmcnt(0)
	v_mfma_f32_16x16x32_bf16 v[118:121], v[202:205], v[168:171], v[118:121]
	v_mfma_f32_16x16x32_bf16 v[114:117], v[210:213], v[168:171], v[114:117]
	v_mfma_f32_16x16x32_bf16 v[102:105], v[202:205], v[176:179], v[102:105]
	v_mfma_f32_16x16x32_bf16 v[98:101], v[210:213], v[176:179], v[98:101]
	v_mfma_f32_16x16x32_bf16 v[86:89], v[202:205], v[184:187], v[86:89]
	v_mfma_f32_16x16x32_bf16 v[82:85], v[210:213], v[184:187], v[82:85]
	v_mfma_f32_16x16x32_bf16 v[70:73], v[202:205], v[192:195], v[70:73]
	v_mfma_f32_16x16x32_bf16 v[66:69], v[210:213], v[192:195], v[66:69]
	v_mfma_f32_16x16x32_bf16 v[118:121], v[206:209], v[172:175], v[118:121]
	v_mfma_f32_16x16x32_bf16 v[114:117], v[214:217], v[172:175], v[114:117]
	v_mfma_f32_16x16x32_bf16 v[102:105], v[206:209], v[180:183], v[102:105]
	v_mfma_f32_16x16x32_bf16 v[98:101], v[214:217], v[180:183], v[98:101]
	v_mfma_f32_16x16x32_bf16 v[86:89], v[206:209], v[188:191], v[86:89]
	v_mfma_f32_16x16x32_bf16 v[82:85], v[214:217], v[188:191], v[82:85]
	v_mfma_f32_16x16x32_bf16 v[70:73], v[206:209], v[198:201], v[70:73]
	v_mfma_f32_16x16x32_bf16 v[66:69], v[214:217], v[198:201], v[66:69]
	s_setprio 0
	s_mov_b32 m0, s59
	v_lshl_add_u64 v[218:219], v[222:223], 0, s[10:11]
	s_barrier
	ds_read_b128 v[168:171], v147 offset:49152
	ds_read_b128 v[172:175], v147 offset:50176
	ds_read_b128 v[176:179], v147 offset:51200
	ds_read_b128 v[180:183], v147 offset:52224
	ds_read_b128 v[184:187], v147 offset:53248
	ds_read_b128 v[188:191], v147 offset:54272
	ds_read_b128 v[192:195], v147 offset:55296
	ds_read_b128 v[198:201], v147 offset:56320
	global_load_lds_dwordx4 v[218:219], off
	v_lshl_add_u64 v[218:219], v[224:225], 0, s[10:11]
	s_mov_b32 m0, s62
	s_nop 0
	global_load_lds_dwordx4 v[218:219], off
	s_barrier
; DI float bflo(unsigned u) { return __uint_as_float(u << 16); }
; DI float bfhi(unsigned u) { return __uint_as_float(u & 0xffff0000u); }
; #define PG8_STAGE(bufoff, gbase, voff) do { _Pragma("unroll") for (int _i = 0; _i < 2; ++_i) \
;         __builtin_amdgcn_global_load_lds((const unsigned*)((const char*)(gbase) + (voff)[_i]), (LAS unsigned*)(lds + (bufoff) + ldsw + _i * 8192), 16, 0, 0); } while (0)
; #define PG8_LDA(dst, b, h) do { _Pragma("unroll") for (int m = 0; m < 4; ++m) _Pragma("unroll") for (int k = 0; k < 2; ++k) dst[m][k] = *(const LAS bf16x8*)(lds + PG8_SA(b, h) + aoff + m * 2048 + k * 1024); } while (0)
; #define PG8_WAIT_V(n) asm volatile("s_waitcnt vmcnt(" #n ")" ::: "memory")
; #define PG8_WAIT_L(n) asm volatile("s_waitcnt lgkmcnt(" #n ")" ::: "memory")
; #define PG8_BAR __builtin_amdgcn_s_barrier()
;     DI void operator()(const f32x4 (&acc)[2][2][4][2], const Unit& u, int wr, int wc, int fr, int fq) const {
;         const int row0 = u.pm * BM + wr * 64 + fr, col0 = u.pn * BM + wc * 32 + 4 * fq;
; #pragma unroll
;         for (int ai = 0; ai < 2; ++ai)
; #pragma unroll
;             for (int m = 0; m < 4; ++m) { const size_t o = (size_t)(row0 + ai * HALF + m * 16) * 1024 + col0;
; #pragma unroll
;                 for (int bj = 0; bj < 2; ++bj)
; #pragma unroll
;                     for (int n = 0; n < 2; ++n) { const size_t oo = o + bj * HALF + n * 16; f32x4 rv;
;                         if (RES_BF16) { const u32x2 t = *(const u32x2*)((const bf16_t*)res + oo); rv = (f32x4){bflo(t.x), bfhi(t.x), bflo(t.y), bfhi(t.y)}; }
; template <class Epi, class Sched>
; DI void gemm_phase(LAS unsigned char* lds, const Gemm g, const Sched& S, const Epi& E) {
;     ...
;             PG8_WAIT_V(6); PG8_BAR; PG8_MMA(1, 1, At, B1); PG8_BAR;
;             PG8_LDB(B0, 1, 0); PG8_SCHED; PG8_LDA(At, 1, 0); PG8_STAGE(PG8_SA(0, 1), a2 + hstep, voffA);
;             PG8_WAIT_L(8); PG8_BAR; PG8_WAIT_L(0); PG8_MMA(0, 0, At, B0); PG8_BAR; PG8_SCHED;
;             PG8_LDB(B1, 1, 1); PG8_STAGE(PG8_SB(1, 0), b3, voffB);
;             PG8_BAR; PG8_WAIT_L(0); PG8_MMA(0, 1, At, B1); PG8_BAR;
;             PG8_LDA(At, 1, 1); PG8_STAGE(PG8_SA(1, 0), a3, voffA);
;             PG8_BAR; PG8_WAIT_L(0); PG8_MMA(1, 0, At, B0); PG8_BAR; PG8_SCHED;
;             PG8_STAGE(PG8_SB(1, 1), b3 + hstep, voffB);
;             PG8_WAIT_V(6); PG8_BAR; PG8_MMA(1, 1, At, B1); PG8_BAR;
	s_waitcnt lgkmcnt(0)
	s_setprio 1
	s_waitcnt lgkmcnt(0)
	v_mfma_f32_16x16x32_bf16 v[62:65], v[140:143], v[168:171], v[62:65]
	v_mfma_f32_16x16x32_bf16 v[58:61], v[154:157], v[168:171], v[58:61]
	v_mfma_f32_16x16x32_bf16 v[46:49], v[140:143], v[176:179], v[46:49]
	v_mfma_f32_16x16x32_bf16 v[42:45], v[154:157], v[176:179], v[42:45]
	v_mfma_f32_16x16x32_bf16 v[30:33], v[140:143], v[184:187], v[30:33]
	v_mfma_f32_16x16x32_bf16 v[26:29], v[154:157], v[184:187], v[26:29]
	v_mfma_f32_16x16x32_bf16 v[14:17], v[140:143], v[192:195], v[14:17]
	v_mfma_f32_16x16x32_bf16 v[10:13], v[154:157], v[192:195], v[10:13]
	v_mfma_f32_16x16x32_bf16 v[62:65], v[150:153], v[172:175], v[62:65]
	v_mfma_f32_16x16x32_bf16 v[58:61], v[158:161], v[172:175], v[58:61]
	v_mfma_f32_16x16x32_bf16 v[46:49], v[150:153], v[180:183], v[46:49]
	v_mfma_f32_16x16x32_bf16 v[42:45], v[158:161], v[180:183], v[42:45]
	v_mfma_f32_16x16x32_bf16 v[30:33], v[150:153], v[188:191], v[30:33]
	v_mfma_f32_16x16x32_bf16 v[26:29], v[158:161], v[188:191], v[26:29]
	v_mfma_f32_16x16x32_bf16 v[14:17], v[150:153], v[198:201], v[14:17]
	v_mfma_f32_16x16x32_bf16 v[10:13], v[158:161], v[198:201], v[10:13]
	s_setprio 0
	s_barrier
	s_add_u32 s50, s50, 0x80080
	s_addc_u32 s51, s51, 0
	s_add_i32 s52, s52, s33
	v_lshl_add_u64 v[140:141], s[50:51], 0, v[132:133]
	s_mov_b32 m0, s52
	s_nop 0
	global_load_lds_dwordx4 v[140:141], off
	v_lshl_add_u64 v[140:141], s[50:51], 0, v[130:131]
	s_add_i32 m0, s52, 0x2000
	s_nop 0
	global_load_lds_dwordx4 v[140:141], off
	s_waitcnt vmcnt(6)
	s_barrier
	s_setprio 1
	v_mfma_f32_16x16x32_bf16 v[54:57], v[202:205], v[168:171], v[54:57]
	v_mfma_f32_16x16x32_bf16 v[50:53], v[210:213], v[168:171], v[50:53]
	v_mfma_f32_16x16x32_bf16 v[38:41], v[202:205], v[176:179], v[38:41]
	v_mfma_f32_16x16x32_bf16 v[34:37], v[210:213], v[176:179], v[34:37]
	v_mfma_f32_16x16x32_bf16 v[22:25], v[202:205], v[184:187], v[22:25]
	v_mfma_f32_16x16x32_bf16 v[18:21], v[210:213], v[184:187], v[18:21]
	v_mfma_f32_16x16x32_bf16 v[6:9], v[202:205], v[192:195], v[6:9]
	v_mfma_f32_16x16x32_bf16 v[2:5], v[210:213], v[192:195], v[2:5]
	v_mfma_f32_16x16x32_bf16 v[54:57], v[206:209], v[172:175], v[54:57]
	v_mfma_f32_16x16x32_bf16 v[50:53], v[214:217], v[172:175], v[50:53]
	v_mfma_f32_16x16x32_bf16 v[38:41], v[206:209], v[180:183], v[38:41]
	v_mfma_f32_16x16x32_bf16 v[34:37], v[214:217], v[180:183], v[34:37]
	v_mfma_f32_16x16x32_bf16 v[22:25], v[206:209], v[188:191], v[22:25]
	v_mfma_f32_16x16x32_bf16 v[18:21], v[214:217], v[188:191], v[18:21]
	v_mfma_f32_16x16x32_bf16 v[6:9], v[206:209], v[198:201], v[6:9]
	v_mfma_f32_16x16x32_bf16 v[2:5], v[214:217], v[198:201], v[2:5]
	s_setprio 0
	s_add_i32 s73, s73, 2
	s_add_u32 s42, s42, 0x100
	s_addc_u32 s43, s43, 0
	s_add_u32 s71, s71, 0x100
	s_addc_u32 s72, s72, 0
	s_cmp_gt_u32 s73, 29
	s_barrier
	s_cbranch_scc0 .LBB0_1523
	v_lshl_add_u32 v236, s56, 8, v144
	v_lshl_or_b32 v237, s84, 9, v149
	v_lshl_or_b32 v236, v236, 11, v237
	s_and_b64 vcc, exec, s[40:41]
	s_mov_b32 s84, s65
	s_mov_b32 s56, s66
	v_mov_b32_e32 v228, v236
	v_add_u32_e32 v229, 0x8000, v236
	v_add_u32_e32 v230, 0x10000, v236
	v_add_u32_e32 v231, 0x18000, v236
	v_add_u32_e32 v232, 0x40000, v236
	v_add_u32_e32 v233, 0x48000, v236
	v_add_u32_e32 v234, 0x50000, v236
	v_add_u32_e32 v235, 0x58000, v236
	global_load_dwordx2 v[140:141], v228, s[48:49]
	global_load_dwordx2 v[142:143], v228, s[48:49] offset:32
	global_load_dwordx2 v[150:151], v228, s[48:49] offset:256
	global_load_dwordx2 v[152:153], v228, s[48:49] offset:288
	global_load_dwordx2 v[154:155], v229, s[48:49]
	global_load_dwordx2 v[156:157], v229, s[48:49] offset:32
	global_load_dwordx2 v[158:159], v229, s[48:49] offset:256
	global_load_dwordx2 v[160:161], v229, s[48:49] offset:288
	global_load_dwordx2 v[168:169], v230, s[48:49]
	global_load_dwordx2 v[170:171], v230, s[48:49] offset:32
	global_load_dwordx2 v[172:173], v230, s[48:49] offset:256
	global_load_dwordx2 v[174:175], v230, s[48:49] offset:288
	global_load_dwordx2 v[176:177], v231, s[48:49]
	global_load_dwordx2 v[178:179], v231, s[48:49] offset:32
	global_load_dwordx2 v[180:181], v231, s[48:49] offset:256
	global_load_dwordx2 v[182:183], v231, s[48:49] offset:288
	global_load_dwordx2 v[184:185], v232, s[48:49]
	global_load_dwordx2 v[186:187], v232, s[48:49] offset:32
	global_load_dwordx2 v[188:189], v232, s[48:49] offset:256
	global_load_dwordx2 v[190:191], v232, s[48:49] offset:288
	global_load_dwordx2 v[192:193], v233, s[48:49]
	global_load_dwordx2 v[194:195], v233, s[48:49] offset:32
	global_load_dwordx2 v[198:199], v233, s[48:49] offset:256
	global_load_dwordx2 v[200:201], v233, s[48:49] offset:288
	global_load_dwordx2 v[202:203], v234, s[48:49]
	global_load_dwordx2 v[204:205], v234, s[48:49] offset:32
	global_load_dwordx2 v[206:207], v234, s[48:49] offset:256
	global_load_dwordx2 v[208:209], v234, s[48:49] offset:288
	global_load_dwordx2 v[210:211], v235, s[48:49]
	global_load_dwordx2 v[212:213], v235, s[48:49] offset:32
	global_load_dwordx2 v[214:215], v235, s[48:49] offset:256
	global_load_dwordx2 v[216:217], v235, s[48:49] offset:288
	s_waitcnt vmcnt(28)
; DI unsigned pk_bf16(float a, float b) { f32x2 v = {a, b}; bf2_t r = __builtin_convertvector(v, bf2_t); return __builtin_bit_cast(unsigned, r); }
; DI float bflo(unsigned u) { return __uint_as_float(u << 16); }
; DI float bfhi(unsigned u) { return __uint_as_float(u & 0xffff0000u); }
;     DI void operator()(const f32x4 (&acc)[2][2][4][2], const Unit& u, int wr, int wc, int fr, int fq) const {
;     ...
;             for (int m = 0; m < 4; ++m) { const size_t o = (size_t)(row0 + ai * HALF + m * 16) * 1024 + col0;
; #pragma unroll
;                 for (int bj = 0; bj < 2; ++bj)
; #pragma unroll
;                     for (int n = 0; n < 2; ++n) { const size_t oo = o + bj * HALF + n * 16; f32x4 rv;
;                         if (RES_BF16) { const u32x2 t = *(const u32x2*)((const bf16_t*)res + oo); rv = (f32x4){bflo(t.x), bfhi(t.x), bflo(t.y), bfhi(t.y)}; }
;                         else rv = *(const f32x4*)((const float*)res + oo);
;                         const f32x4 v = acc[ai][bj][m][n] + rv; u32x2 w; w.x = pk_bf16(v.x, v.y); w.y = pk_bf16(v.z, v.w);
;                         *(u32x2*)(O + oo) = w; } }
	v_lshlrev_b32_e32 v226, 16, v141
	v_and_b32_e32 v227, 0xffff0000, v141
	v_and_b32_e32 v141, 0xffff0000, v140
	v_lshlrev_b32_e32 v140, 16, v140
	v_pk_add_f32 v[128:129], v[128:129], v[226:227]
	v_pk_add_f32 v[126:127], v[126:127], v[140:141]
	v_lshlrev_b32_e32 v240, 16, v143
	v_and_b32_e32 v241, 0xffff0000, v143
	v_and_b32_e32 v143, 0xffff0000, v142
	v_lshlrev_b32_e32 v142, 16, v142
	v_pk_add_f32 v[124:125], v[124:125], v[240:241]
	v_pk_add_f32 v[122:123], v[122:123], v[142:143]
	v_lshlrev_b32_e32 v226, 16, v151
	v_and_b32_e32 v227, 0xffff0000, v151
	v_and_b32_e32 v151, 0xffff0000, v150
	v_lshlrev_b32_e32 v150, 16, v150
	v_pk_add_f32 v[120:121], v[120:121], v[226:227]
	v_pk_add_f32 v[118:119], v[118:119], v[150:151]
	v_lshlrev_b32_e32 v240, 16, v153
	v_and_b32_e32 v241, 0xffff0000, v153
	v_and_b32_e32 v153, 0xffff0000, v152
	v_lshlrev_b32_e32 v152, 16, v152
	v_pk_add_f32 v[116:117], v[116:117], v[240:241]
	v_pk_add_f32 v[114:115], v[114:115], v[152:153]
	v_cvt_pk_bf16_f32 v126, v126, v127
	v_cvt_pk_bf16_f32 v127, v128, v129
	v_cvt_pk_bf16_f32 v122, v122, v123
	v_cvt_pk_bf16_f32 v123, v124, v125
	v_cvt_pk_bf16_f32 v118, v118, v119
	v_cvt_pk_bf16_f32 v119, v120, v121
	v_cvt_pk_bf16_f32 v114, v114, v115
	v_cvt_pk_bf16_f32 v115, v116, v117
	global_store_dwordx2 v228, v[126:127], s[8:9]
	global_store_dwordx2 v228, v[122:123], s[8:9] offset:32
	global_store_dwordx2 v228, v[118:119], s[8:9] offset:256
	global_store_dwordx2 v228, v[114:115], s[8:9] offset:288
	s_waitcnt vmcnt(28)
	v_lshlrev_b32_e32 v226, 16, v155
	v_and_b32_e32 v227, 0xffff0000, v155
	v_and_b32_e32 v155, 0xffff0000, v154
	v_lshlrev_b32_e32 v154, 16, v154
	v_pk_add_f32 v[112:113], v[112:113], v[226:227]
	v_pk_add_f32 v[110:111], v[110:111], v[154:155]
	v_lshlrev_b32_e32 v240, 16, v157
	v_and_b32_e32 v241, 0xffff0000, v157
	v_and_b32_e32 v157, 0xffff0000, v156
	v_lshlrev_b32_e32 v156, 16, v156
	v_pk_add_f32 v[108:109], v[108:109], v[240:241]
	v_pk_add_f32 v[106:107], v[106:107], v[156:157]
	v_lshlrev_b32_e32 v226, 16, v159
	v_and_b32_e32 v227, 0xffff0000, v159
	v_and_b32_e32 v159, 0xffff0000, v158
	v_lshlrev_b32_e32 v158, 16, v158
	v_pk_add_f32 v[104:105], v[104:105], v[226:227]
	v_pk_add_f32 v[102:103], v[102:103], v[158:159]
	v_lshlrev_b32_e32 v240, 16, v161
	v_and_b32_e32 v241, 0xffff0000, v161
	v_and_b32_e32 v161, 0xffff0000, v160
	v_lshlrev_b32_e32 v160, 16, v160
	v_pk_add_f32 v[100:101], v[100:101], v[240:241]
	v_pk_add_f32 v[98:99], v[98:99], v[160:161]
	v_cvt_pk_bf16_f32 v110, v110, v111
	v_cvt_pk_bf16_f32 v111, v112, v113
	v_cvt_pk_bf16_f32 v106, v106, v107
	v_cvt_pk_bf16_f32 v107, v108, v109
	v_cvt_pk_bf16_f32 v102, v102, v103
	v_cvt_pk_bf16_f32 v103, v104, v105
	v_cvt_pk_bf16_f32 v98, v98, v99
	v_cvt_pk_bf16_f32 v99, v100, v101
	global_store_dwordx2 v229, v[110:111], s[8:9]
	global_store_dwordx2 v229, v[106:107], s[8:9] offset:32
	global_store_dwordx2 v229, v[102:103], s[8:9] offset:256
	global_store_dwordx2 v229, v[98:99], s[8:9] offset:288
	s_waitcnt vmcnt(28)
	v_lshlrev_b32_e32 v226, 16, v169
	v_and_b32_e32 v227, 0xffff0000, v169
	v_and_b32_e32 v169, 0xffff0000, v168
	v_lshlrev_b32_e32 v168, 16, v168
	v_pk_add_f32 v[96:97], v[96:97], v[226:227]
	v_pk_add_f32 v[94:95], v[94:95], v[168:169]
	v_lshlrev_b32_e32 v240, 16, v171
	v_and_b32_e32 v241, 0xffff0000, v171
	v_and_b32_e32 v171, 0xffff0000, v170
	v_lshlrev_b32_e32 v170, 16, v170
	v_pk_add_f32 v[92:93], v[92:93], v[240:241]
	v_pk_add_f32 v[90:91], v[90:91], v[170:171]
	v_lshlrev_b32_e32 v226, 16, v173
	v_and_b32_e32 v227, 0xffff0000, v173
	v_and_b32_e32 v173, 0xffff0000, v172
	v_lshlrev_b32_e32 v172, 16, v172
	v_pk_add_f32 v[88:89], v[88:89], v[226:227]
	v_pk_add_f32 v[86:87], v[86:87], v[172:173]
	v_lshlrev_b32_e32 v240, 16, v175
	v_and_b32_e32 v241, 0xffff0000, v175
	v_and_b32_e32 v175, 0xffff0000, v174
	v_lshlrev_b32_e32 v174, 16, v174
	v_pk_add_f32 v[84:85], v[84:85], v[240:241]
	v_pk_add_f32 v[82:83], v[82:83], v[174:175]
	v_cvt_pk_bf16_f32 v94, v94, v95
	v_cvt_pk_bf16_f32 v95, v96, v97
	v_cvt_pk_bf16_f32 v90, v90, v91
	v_cvt_pk_bf16_f32 v91, v92, v93
	v_cvt_pk_bf16_f32 v86, v86, v87
	v_cvt_pk_bf16_f32 v87, v88, v89
	v_cvt_pk_bf16_f32 v82, v82, v83
	v_cvt_pk_bf16_f32 v83, v84, v85
	global_store_dwordx2 v230, v[94:95], s[8:9]
	global_store_dwordx2 v230, v[90:91], s[8:9] offset:32
	global_store_dwordx2 v230, v[86:87], s[8:9] offset:256
	global_store_dwordx2 v230, v[82:83], s[8:9] offset:288
	s_waitcnt vmcnt(28)
	v_lshlrev_b32_e32 v226, 16, v177
	v_and_b32_e32 v227, 0xffff0000, v177
	v_and_b32_e32 v177, 0xffff0000, v176
	v_lshlrev_b32_e32 v176, 16, v176
	v_pk_add_f32 v[80:81], v[80:81], v[226:227]
	v_pk_add_f32 v[78:79], v[78:79], v[176:177]
	v_lshlrev_b32_e32 v240, 16, v179
	v_and_b32_e32 v241, 0xffff0000, v179
	v_and_b32_e32 v179, 0xffff0000, v178
	v_lshlrev_b32_e32 v178, 16, v178
	v_pk_add_f32 v[76:77], v[76:77], v[240:241]
	v_pk_add_f32 v[74:75], v[74:75], v[178:179]
	v_lshlrev_b32_e32 v226, 16, v181
	v_and_b32_e32 v227, 0xffff0000, v181
	v_and_b32_e32 v181, 0xffff0000, v180
	v_lshlrev_b32_e32 v180, 16, v180
	v_pk_add_f32 v[72:73], v[72:73], v[226:227]
	v_pk_add_f32 v[70:71], v[70:71], v[180:181]
	v_lshlrev_b32_e32 v240, 16, v183
	v_and_b32_e32 v241, 0xffff0000, v183
	v_and_b32_e32 v183, 0xffff0000, v182
	v_lshlrev_b32_e32 v182, 16, v182
	v_pk_add_f32 v[68:69], v[68:69], v[240:241]
	v_pk_add_f32 v[66:67], v[66:67], v[182:183]
	v_cvt_pk_bf16_f32 v78, v78, v79
	v_cvt_pk_bf16_f32 v79, v80, v81
	v_cvt_pk_bf16_f32 v74, v74, v75
	v_cvt_pk_bf16_f32 v75, v76, v77
	v_cvt_pk_bf16_f32 v70, v70, v71
	v_cvt_pk_bf16_f32 v71, v72, v73
	v_cvt_pk_bf16_f32 v66, v66, v67
	v_cvt_pk_bf16_f32 v67, v68, v69
	global_store_dwordx2 v231, v[78:79], s[8:9]
	global_store_dwordx2 v231, v[74:75], s[8:9] offset:32
	global_store_dwordx2 v231, v[70:71], s[8:9] offset:256
	global_store_dwordx2 v231, v[66:67], s[8:9] offset:288
	s_waitcnt vmcnt(28)
; DI unsigned pk_bf16(float a, float b) { f32x2 v = {a, b}; bf2_t r = __builtin_convertvector(v, bf2_t); return __builtin_bit_cast(unsigned, r); }
; DI float bflo(unsigned u) { return __uint_as_float(u << 16); }
; DI float bfhi(unsigned u) { return __uint_as_float(u & 0xffff0000u); }
; #define PG8_WAIT_V(n) asm volatile("s_waitcnt vmcnt(" #n ")" ::: "memory")
; #define PG8_BAR __builtin_amdgcn_s_barrier()
;     DI void operator()(const f32x4 (&acc)[2][2][4][2], const Unit& u, int wr, int wc, int fr, int fq) const {
;     ...
;             for (int m = 0; m < 4; ++m) { const size_t o = (size_t)(row0 + ai * HALF + m * 16) * 1024 + col0;
; #pragma unroll
;                 for (int bj = 0; bj < 2; ++bj)
; #pragma unroll
;                     for (int n = 0; n < 2; ++n) { const size_t oo = o + bj * HALF + n * 16; f32x4 rv;
;                         if (RES_BF16) { const u32x2 t = *(const u32x2*)((const bf16_t*)res + oo); rv = (f32x4){bflo(t.x), bfhi(t.x), bflo(t.y), bfhi(t.y)}; }
;                         else rv = *(const f32x4*)((const float*)res + oo);
;                         const f32x4 v = acc[ai][bj][m][n] + rv; u32x2 w; w.x = pk_bf16(v.x, v.y); w.y = pk_bf16(v.z, v.w);
;                         *(u32x2*)(O + oo) = w; } }
; template <class Epi, class Sched>
; DI void gemm_phase(LAS unsigned char* lds, const Gemm g, const Sched& S, const Epi& E) {
;     ...
;         if (!has_next) break;
; #pragma unroll
;         for (int a = 0; a < 2; ++a)
; #pragma unroll
;             for (int b = 0; b < 2; ++b)
; #pragma unroll
;                 for (int m = 0; m < 4; ++m)
; #pragma unroll
;                     for (int n = 0; n < 2; ++n) acc[a][b][m][n] = (f32x4){0.f, 0.f, 0.f, 0.f};
;         cur = nxt; cA = nA; cB = nB; ++ui;
;     }
;     PG8_WAIT_V(0);
;     if (wr == 0) PG8_BAR;
;     PG8_BAR;
	v_lshlrev_b32_e32 v226, 16, v185
	v_and_b32_e32 v227, 0xffff0000, v185
	v_and_b32_e32 v185, 0xffff0000, v184
	v_lshlrev_b32_e32 v184, 16, v184
	v_pk_add_f32 v[64:65], v[64:65], v[226:227]
	v_pk_add_f32 v[62:63], v[62:63], v[184:185]
	v_lshlrev_b32_e32 v240, 16, v187
	v_and_b32_e32 v241, 0xffff0000, v187
	v_and_b32_e32 v187, 0xffff0000, v186
	v_lshlrev_b32_e32 v186, 16, v186
	v_pk_add_f32 v[60:61], v[60:61], v[240:241]
	v_pk_add_f32 v[58:59], v[58:59], v[186:187]
	v_lshlrev_b32_e32 v226, 16, v189
	v_and_b32_e32 v227, 0xffff0000, v189
	v_and_b32_e32 v189, 0xffff0000, v188
	v_lshlrev_b32_e32 v188, 16, v188
	v_pk_add_f32 v[56:57], v[56:57], v[226:227]
	v_pk_add_f32 v[54:55], v[54:55], v[188:189]
	v_lshlrev_b32_e32 v240, 16, v191
	v_and_b32_e32 v241, 0xffff0000, v191
	v_and_b32_e32 v191, 0xffff0000, v190
	v_lshlrev_b32_e32 v190, 16, v190
	v_pk_add_f32 v[52:53], v[52:53], v[240:241]
	v_pk_add_f32 v[50:51], v[50:51], v[190:191]
	v_cvt_pk_bf16_f32 v62, v62, v63
	v_cvt_pk_bf16_f32 v63, v64, v65
	v_cvt_pk_bf16_f32 v58, v58, v59
	v_cvt_pk_bf16_f32 v59, v60, v61
	v_cvt_pk_bf16_f32 v54, v54, v55
	v_cvt_pk_bf16_f32 v55, v56, v57
	v_cvt_pk_bf16_f32 v50, v50, v51
	v_cvt_pk_bf16_f32 v51, v52, v53
	global_store_dwordx2 v232, v[62:63], s[8:9]
	global_store_dwordx2 v232, v[58:59], s[8:9] offset:32
	global_store_dwordx2 v232, v[54:55], s[8:9] offset:256
	global_store_dwordx2 v232, v[50:51], s[8:9] offset:288
	s_waitcnt vmcnt(28)
	v_lshlrev_b32_e32 v226, 16, v193
	v_and_b32_e32 v227, 0xffff0000, v193
	v_and_b32_e32 v193, 0xffff0000, v192
	v_lshlrev_b32_e32 v192, 16, v192
	v_pk_add_f32 v[48:49], v[48:49], v[226:227]
	v_pk_add_f32 v[46:47], v[46:47], v[192:193]
	v_lshlrev_b32_e32 v240, 16, v195
	v_and_b32_e32 v241, 0xffff0000, v195
	v_and_b32_e32 v195, 0xffff0000, v194
	v_lshlrev_b32_e32 v194, 16, v194
	v_pk_add_f32 v[44:45], v[44:45], v[240:241]
	v_pk_add_f32 v[42:43], v[42:43], v[194:195]
	v_lshlrev_b32_e32 v226, 16, v199
	v_and_b32_e32 v227, 0xffff0000, v199
	v_and_b32_e32 v199, 0xffff0000, v198
	v_lshlrev_b32_e32 v198, 16, v198
	v_pk_add_f32 v[40:41], v[40:41], v[226:227]
	v_pk_add_f32 v[38:39], v[38:39], v[198:199]
	v_lshlrev_b32_e32 v240, 16, v201
	v_and_b32_e32 v241, 0xffff0000, v201
	v_and_b32_e32 v201, 0xffff0000, v200
	v_lshlrev_b32_e32 v200, 16, v200
	v_pk_add_f32 v[36:37], v[36:37], v[240:241]
	v_pk_add_f32 v[34:35], v[34:35], v[200:201]
	v_cvt_pk_bf16_f32 v46, v46, v47
	v_cvt_pk_bf16_f32 v47, v48, v49
	v_cvt_pk_bf16_f32 v42, v42, v43
	v_cvt_pk_bf16_f32 v43, v44, v45
	v_cvt_pk_bf16_f32 v38, v38, v39
	v_cvt_pk_bf16_f32 v39, v40, v41
	v_cvt_pk_bf16_f32 v34, v34, v35
	v_cvt_pk_bf16_f32 v35, v36, v37
	global_store_dwordx2 v233, v[46:47], s[8:9]
	global_store_dwordx2 v233, v[42:43], s[8:9] offset:32
	global_store_dwordx2 v233, v[38:39], s[8:9] offset:256
	global_store_dwordx2 v233, v[34:35], s[8:9] offset:288
	s_waitcnt vmcnt(28)
	v_lshlrev_b32_e32 v226, 16, v203
	v_and_b32_e32 v227, 0xffff0000, v203
	v_and_b32_e32 v203, 0xffff0000, v202
	v_lshlrev_b32_e32 v202, 16, v202
	v_pk_add_f32 v[32:33], v[32:33], v[226:227]
	v_pk_add_f32 v[30:31], v[30:31], v[202:203]
	v_lshlrev_b32_e32 v240, 16, v205
	v_and_b32_e32 v241, 0xffff0000, v205
	v_and_b32_e32 v205, 0xffff0000, v204
	v_lshlrev_b32_e32 v204, 16, v204
	v_pk_add_f32 v[28:29], v[28:29], v[240:241]
	v_pk_add_f32 v[26:27], v[26:27], v[204:205]
	v_lshlrev_b32_e32 v226, 16, v207
	v_and_b32_e32 v227, 0xffff0000, v207
	v_and_b32_e32 v207, 0xffff0000, v206
	v_lshlrev_b32_e32 v206, 16, v206
	v_pk_add_f32 v[24:25], v[24:25], v[226:227]
	v_pk_add_f32 v[22:23], v[22:23], v[206:207]
	v_lshlrev_b32_e32 v240, 16, v209
	v_and_b32_e32 v241, 0xffff0000, v209
	v_and_b32_e32 v209, 0xffff0000, v208
	v_lshlrev_b32_e32 v208, 16, v208
	v_pk_add_f32 v[20:21], v[20:21], v[240:241]
	v_pk_add_f32 v[18:19], v[18:19], v[208:209]
	v_cvt_pk_bf16_f32 v30, v30, v31
	v_cvt_pk_bf16_f32 v31, v32, v33
	v_cvt_pk_bf16_f32 v26, v26, v27
	v_cvt_pk_bf16_f32 v27, v28, v29
	v_cvt_pk_bf16_f32 v22, v22, v23
	v_cvt_pk_bf16_f32 v23, v24, v25
	v_cvt_pk_bf16_f32 v18, v18, v19
	v_cvt_pk_bf16_f32 v19, v20, v21
	global_store_dwordx2 v234, v[30:31], s[8:9]
	global_store_dwordx2 v234, v[26:27], s[8:9] offset:32
	global_store_dwordx2 v234, v[22:23], s[8:9] offset:256
	global_store_dwordx2 v234, v[18:19], s[8:9] offset:288
	s_waitcnt vmcnt(28)
	v_lshlrev_b32_e32 v226, 16, v211
	v_and_b32_e32 v227, 0xffff0000, v211
	v_and_b32_e32 v211, 0xffff0000, v210
	v_lshlrev_b32_e32 v210, 16, v210
	v_pk_add_f32 v[16:17], v[16:17], v[226:227]
	v_pk_add_f32 v[14:15], v[14:15], v[210:211]
	v_lshlrev_b32_e32 v240, 16, v213
	v_and_b32_e32 v241, 0xffff0000, v213
	v_and_b32_e32 v213, 0xffff0000, v212
	v_lshlrev_b32_e32 v212, 16, v212
	v_pk_add_f32 v[12:13], v[12:13], v[240:241]
	v_pk_add_f32 v[10:11], v[10:11], v[212:213]
	v_lshlrev_b32_e32 v226, 16, v215
	v_and_b32_e32 v227, 0xffff0000, v215
	v_and_b32_e32 v215, 0xffff0000, v214
	v_lshlrev_b32_e32 v214, 16, v214
	v_pk_add_f32 v[8:9], v[8:9], v[226:227]
	v_pk_add_f32 v[6:7], v[6:7], v[214:215]
	v_lshlrev_b32_e32 v240, 16, v217
	v_and_b32_e32 v241, 0xffff0000, v217
	v_and_b32_e32 v217, 0xffff0000, v216
	v_lshlrev_b32_e32 v216, 16, v216
	v_pk_add_f32 v[4:5], v[4:5], v[240:241]
	v_pk_add_f32 v[2:3], v[2:3], v[216:217]
	v_cvt_pk_bf16_f32 v14, v14, v15
	v_cvt_pk_bf16_f32 v15, v16, v17
	v_cvt_pk_bf16_f32 v10, v10, v11
	v_cvt_pk_bf16_f32 v11, v12, v13
	v_cvt_pk_bf16_f32 v6, v6, v7
	v_cvt_pk_bf16_f32 v7, v8, v9
	v_cvt_pk_bf16_f32 v2, v2, v3
	v_cvt_pk_bf16_f32 v3, v4, v5
	global_store_dwordx2 v235, v[14:15], s[8:9]
	global_store_dwordx2 v235, v[10:11], s[8:9] offset:32
	global_store_dwordx2 v235, v[6:7], s[8:9] offset:256
	global_store_dwordx2 v235, v[2:3], s[8:9] offset:288
	s_cbranch_vccz .LBB0_1522
	s_waitcnt vmcnt(0)
	s_cmpk_gt_u32 s3, 0xff
	s_cbranch_scc1 .LBB0_1527
	s_barrier
